# GEMM K-loops: per-interval s_setprio flips removed, one static s_setprio 1 for the lag half (waves 4-7), reset at epilogue
# speedup vs baseline: 1.0156x; 1.0095x over previous
.LBB0_127:
	s_ashr_i32 s13, s12, 31
	s_lshl_b64 s[0:1], s[12:13], 19
	s_add_u32 s42, s6, s0
	v_cmp_lt_i64_e32 vcc, s[34:35], v[236:237]
	s_addc_u32 s43, s7, s1
	s_and_b64 s[0:1], vcc, exec
	s_cselect_b32 s0, s43, s19
	s_cselect_b32 s1, s42, s18
	s_ashr_i32 s31, s30, 31
	s_lshl_b64 s[24:25], s[30:31], 19
	s_add_u32 s44, s16, s24
	s_addc_u32 s45, s17, s25
	s_and_b64 s[24:25], vcc, exec
	s_cselect_b32 s13, s45, s15
	s_cselect_b32 s24, s44, s14
	s_add_u32 vcc_lo, s18, 0x40080
	s_addc_u32 vcc_hi, s19, 0
	s_add_u32 s25, s14, 0x100
	v_mov_b32_e32 v0, 0
	s_addc_u32 s31, s15, 0
	s_mov_b32 s34, -2
	v_mov_b32_e32 v1, v0
	v_mov_b32_e32 v2, v0
	v_mov_b32_e32 v3, v0
	v_mov_b32_e32 v4, v0
	v_mov_b32_e32 v5, v0
	v_mov_b32_e32 v6, v0
	v_mov_b32_e32 v7, v0
	v_mov_b32_e32 v16, v0
	v_mov_b32_e32 v17, v0
	v_mov_b32_e32 v18, v0
	v_mov_b32_e32 v19, v0
	v_mov_b32_e32 v20, v0
	v_mov_b32_e32 v21, v0
	v_mov_b32_e32 v22, v0
	v_mov_b32_e32 v23, v0
	v_mov_b32_e32 v32, v0
	v_mov_b32_e32 v33, v0
	v_mov_b32_e32 v34, v0
	v_mov_b32_e32 v35, v0
	v_mov_b32_e32 v36, v0
	v_mov_b32_e32 v37, v0
	v_mov_b32_e32 v38, v0
	v_mov_b32_e32 v39, v0
	v_mov_b32_e32 v48, v0
	v_mov_b32_e32 v49, v0
	v_mov_b32_e32 v50, v0
	v_mov_b32_e32 v51, v0
	v_mov_b32_e32 v52, v0
	v_mov_b32_e32 v53, v0
	v_mov_b32_e32 v54, v0
	v_mov_b32_e32 v55, v0
	v_mov_b32_e32 v8, v0
	v_mov_b32_e32 v9, v0
	v_mov_b32_e32 v10, v0
	v_mov_b32_e32 v11, v0
	v_mov_b32_e32 v12, v0
	v_mov_b32_e32 v13, v0
	v_mov_b32_e32 v14, v0
	v_mov_b32_e32 v15, v0
	v_mov_b32_e32 v24, v0
	v_mov_b32_e32 v25, v0
	v_mov_b32_e32 v26, v0
	v_mov_b32_e32 v27, v0
	v_mov_b32_e32 v28, v0
	v_mov_b32_e32 v29, v0
	v_mov_b32_e32 v30, v0
	v_mov_b32_e32 v31, v0
	v_mov_b32_e32 v40, v0
	v_mov_b32_e32 v41, v0
	v_mov_b32_e32 v42, v0
	v_mov_b32_e32 v43, v0
	v_mov_b32_e32 v44, v0
	v_mov_b32_e32 v45, v0
	v_mov_b32_e32 v46, v0
	v_mov_b32_e32 v47, v0
	v_mov_b32_e32 v56, v0
	v_mov_b32_e32 v57, v0
	v_mov_b32_e32 v58, v0
	v_mov_b32_e32 v59, v0
	v_mov_b32_e32 v60, v0
	v_mov_b32_e32 v61, v0
	v_mov_b32_e32 v62, v0
	v_mov_b32_e32 v63, v0
	v_mov_b32_e32 v64, v0
	v_mov_b32_e32 v65, v0
	v_mov_b32_e32 v66, v0
	v_mov_b32_e32 v67, v0
	v_mov_b32_e32 v68, v0
	v_mov_b32_e32 v69, v0
	v_mov_b32_e32 v70, v0
	v_mov_b32_e32 v71, v0
	v_mov_b32_e32 v80, v0
	v_mov_b32_e32 v81, v0
	v_mov_b32_e32 v82, v0
	v_mov_b32_e32 v83, v0
	v_mov_b32_e32 v84, v0
	v_mov_b32_e32 v85, v0
	v_mov_b32_e32 v86, v0
	v_mov_b32_e32 v87, v0
	v_mov_b32_e32 v96, v0
	v_mov_b32_e32 v97, v0
	v_mov_b32_e32 v98, v0
	v_mov_b32_e32 v99, v0
	v_mov_b32_e32 v100, v0
	v_mov_b32_e32 v101, v0
	v_mov_b32_e32 v102, v0
	v_mov_b32_e32 v103, v0
	v_mov_b32_e32 v112, v0
	v_mov_b32_e32 v113, v0
	v_mov_b32_e32 v114, v0
	v_mov_b32_e32 v115, v0
	v_mov_b32_e32 v116, v0
	v_mov_b32_e32 v117, v0
	v_mov_b32_e32 v118, v0
	v_mov_b32_e32 v119, v0
	v_mov_b32_e32 v72, v0
	v_mov_b32_e32 v73, v0
	v_mov_b32_e32 v74, v0
	v_mov_b32_e32 v75, v0
	v_mov_b32_e32 v76, v0
	v_mov_b32_e32 v77, v0
	v_mov_b32_e32 v78, v0
	v_mov_b32_e32 v79, v0
	v_mov_b32_e32 v88, v0
	v_mov_b32_e32 v89, v0
	v_mov_b32_e32 v90, v0
	v_mov_b32_e32 v91, v0
	v_mov_b32_e32 v92, v0
	v_mov_b32_e32 v93, v0
	v_mov_b32_e32 v94, v0
	v_mov_b32_e32 v95, v0
	v_mov_b32_e32 v104, v0
	v_mov_b32_e32 v105, v0
	v_mov_b32_e32 v106, v0
	v_mov_b32_e32 v107, v0
	v_mov_b32_e32 v108, v0
	v_mov_b32_e32 v109, v0
	v_mov_b32_e32 v110, v0
	v_mov_b32_e32 v111, v0
	v_mov_b32_e32 v120, v0
	v_mov_b32_e32 v121, v0
	v_mov_b32_e32 v122, v0
	v_mov_b32_e32 v123, v0
	v_mov_b32_e32 v124, v0
	v_mov_b32_e32 v125, v0
	v_mov_b32_e32 v126, v0
	v_mov_b32_e32 v127, v0
	s_cmpk_gt_u32 s50, 0xff
	s_cbranch_scc0 .Lgout_enter
	s_barrier
	s_setprio 1
.Lgout_enter:
.LBB0_128:
	s_add_u32 s14, vcc_lo, 0xfffc0080
	s_addc_u32 s15, vcc_hi, -1
	s_add_i32 s20, 16, 0x10000
	v_add_u32_e32 v130, s20, v160
	ds_read_b128 v[154:157], v130
	ds_read_b128 v[164:167], v130 offset:1024
	ds_read_b128 v[168:171], v130 offset:2048
	ds_read_b128 v[172:175], v130 offset:3072
	s_cmp_eq_u32 s34, 12
	s_cselect_b32 s19, s0, s15
	s_cselect_b32 s18, s1, s14
	s_cselect_b32 s15, s13, s31
	s_cselect_b32 s14, s24, s25
	v_lshl_add_u64 v[130:131], vcc, 0, v[150:151]
	s_add_i32 m0, s9, 0xc000
	ds_read_b128 v[176:179], v162
	ds_read_b128 v[180:183], v162 offset:1024
	ds_read_b128 v[184:187], v162 offset:2048
	ds_read_b128 v[188:191], v162 offset:3072
	ds_read_b128 v[192:195], v162 offset:4096
	ds_read_b128 v[196:199], v162 offset:5120
	ds_read_b128 v[200:203], v162 offset:6144
	ds_read_b128 v[204:207], v162 offset:7168
	global_load_lds_dwordx4 v[130:131], off
	v_lshl_add_u64 v[130:131], vcc, 0, v[152:153]
	s_add_i32 m0, s9, 0xe000
	s_nop 0
	global_load_lds_dwordx4 v[130:131], off
	s_add_i32 s35, 16, 0x14000
	v_add_u32_e32 v130, s35, v160
	ds_read_b128 v[208:211], v130
	ds_read_b128 v[212:215], v130 offset:1024
	ds_read_b128 v[216:219], v130 offset:2048
	ds_read_b128 v[220:223], v130 offset:3072
	s_waitcnt vmcnt(8) lgkmcnt(0)
	s_barrier
	v_mfma_f32_16x16x32_bf16 v[124:127], v[154:157], v[176:179], v[124:127]
	v_mfma_f32_16x16x32_bf16 v[120:123], v[168:171], v[176:179], v[120:123]
	v_mfma_f32_16x16x32_bf16 v[108:111], v[154:157], v[184:187], v[108:111]
	v_mfma_f32_16x16x32_bf16 v[104:107], v[168:171], v[184:187], v[104:107]
	v_mfma_f32_16x16x32_bf16 v[92:95], v[154:157], v[192:195], v[92:95]
	v_mfma_f32_16x16x32_bf16 v[88:91], v[168:171], v[192:195], v[88:91]
	v_mfma_f32_16x16x32_bf16 v[76:79], v[154:157], v[200:203], v[76:79]
	v_mfma_f32_16x16x32_bf16 v[72:75], v[168:171], v[200:203], v[72:75]
	v_mfma_f32_16x16x32_bf16 v[124:127], v[164:167], v[180:183], v[124:127]
	v_mfma_f32_16x16x32_bf16 v[120:123], v[172:175], v[180:183], v[120:123]
	v_mfma_f32_16x16x32_bf16 v[108:111], v[164:167], v[188:191], v[108:111]
	v_mfma_f32_16x16x32_bf16 v[104:107], v[172:175], v[188:191], v[104:107]
	v_mfma_f32_16x16x32_bf16 v[92:95], v[164:167], v[196:199], v[92:95]
	v_mfma_f32_16x16x32_bf16 v[88:91], v[172:175], v[196:199], v[88:91]
	v_mfma_f32_16x16x32_bf16 v[76:79], v[164:167], v[204:207], v[76:79]
	v_mfma_f32_16x16x32_bf16 v[72:75], v[172:175], v[204:207], v[72:75]
	v_mfma_f32_16x16x32_bf16 v[116:119], v[208:211], v[176:179], v[116:119]
	v_mfma_f32_16x16x32_bf16 v[112:115], v[216:219], v[176:179], v[112:115]
	v_mfma_f32_16x16x32_bf16 v[100:103], v[208:211], v[184:187], v[100:103]
	v_mfma_f32_16x16x32_bf16 v[96:99], v[216:219], v[184:187], v[96:99]
	v_mfma_f32_16x16x32_bf16 v[84:87], v[208:211], v[192:195], v[84:87]
	v_mfma_f32_16x16x32_bf16 v[80:83], v[216:219], v[192:195], v[80:83]
	v_mfma_f32_16x16x32_bf16 v[68:71], v[208:211], v[200:203], v[68:71]
	v_mfma_f32_16x16x32_bf16 v[64:67], v[216:219], v[200:203], v[64:67]
	v_mfma_f32_16x16x32_bf16 v[116:119], v[212:215], v[180:183], v[116:119]
	v_mfma_f32_16x16x32_bf16 v[112:115], v[220:223], v[180:183], v[112:115]
	v_mfma_f32_16x16x32_bf16 v[100:103], v[212:215], v[188:191], v[100:103]
	v_mfma_f32_16x16x32_bf16 v[96:99], v[220:223], v[188:191], v[96:99]
	v_mfma_f32_16x16x32_bf16 v[84:87], v[212:215], v[196:199], v[84:87]
	v_mfma_f32_16x16x32_bf16 v[80:83], v[220:223], v[196:199], v[80:83]
	v_mfma_f32_16x16x32_bf16 v[68:71], v[212:215], v[204:207], v[68:71]
	v_mfma_f32_16x16x32_bf16 v[64:67], v[220:223], v[204:207], v[64:67]
	s_barrier
	ds_read_b128 v[176:179], v162 offset:16384
	ds_read_b128 v[180:183], v162 offset:17408
	ds_read_b128 v[184:187], v162 offset:18432
	ds_read_b128 v[188:191], v162 offset:19456
	ds_read_b128 v[192:195], v162 offset:20480
	ds_read_b128 v[196:199], v162 offset:21504
	ds_read_b128 v[200:203], v162 offset:22528
	ds_read_b128 v[204:207], v162 offset:23552
	s_add_i32 s20, s20, s5
	v_lshl_add_u64 v[130:131], s[14:15], 0, v[128:129]
	s_mov_b32 m0, s20
	v_lshl_add_u64 v[132:133], s[14:15], 0, v[148:149]
	global_load_lds_dwordx4 v[130:131], off
	s_add_i32 m0, s20, 0x2000
	s_nop 0
	global_load_lds_dwordx4 v[132:133], off
	s_mov_b32 m0, s9
	v_lshl_add_u64 v[134:135], s[18:19], 0, v[144:145]
	global_load_lds_dwordx4 v[134:135], off
	v_lshl_add_u64 v[136:137], s[18:19], 0, v[146:147]
	s_mov_b32 m0, s36
	s_nop 0
	global_load_lds_dwordx4 v[136:137], off
	s_add_u32 s48, s14, 0x40000
	s_addc_u32 s49, s15, 0
	s_add_i32 s20, s35, s5
	v_lshl_add_u64 v[138:139], s[48:49], 0, v[128:129]
	s_mov_b32 m0, s20
	s_nop 0
	global_load_lds_dwordx4 v[138:139], off
	v_lshl_add_u64 v[138:139], s[48:49], 0, v[148:149]
	s_add_i32 m0, s20, 0x2000
	s_nop 0
	global_load_lds_dwordx4 v[138:139], off
	s_waitcnt vmcnt(8) lgkmcnt(0)
	s_barrier
	v_mfma_f32_16x16x32_bf16 v[60:63], v[154:157], v[176:179], v[60:63]
	v_mfma_f32_16x16x32_bf16 v[56:59], v[168:171], v[176:179], v[56:59]
	v_mfma_f32_16x16x32_bf16 v[44:47], v[154:157], v[184:187], v[44:47]
	v_mfma_f32_16x16x32_bf16 v[40:43], v[168:171], v[184:187], v[40:43]
	v_mfma_f32_16x16x32_bf16 v[28:31], v[154:157], v[192:195], v[28:31]
	v_mfma_f32_16x16x32_bf16 v[24:27], v[168:171], v[192:195], v[24:27]
	v_mfma_f32_16x16x32_bf16 v[12:15], v[154:157], v[200:203], v[12:15]
	v_mfma_f32_16x16x32_bf16 v[8:11], v[168:171], v[200:203], v[8:11]
	v_mfma_f32_16x16x32_bf16 v[60:63], v[164:167], v[180:183], v[60:63]
	v_mfma_f32_16x16x32_bf16 v[56:59], v[172:175], v[180:183], v[56:59]
	v_mfma_f32_16x16x32_bf16 v[44:47], v[164:167], v[188:191], v[44:47]
	v_mfma_f32_16x16x32_bf16 v[40:43], v[172:175], v[188:191], v[40:43]
	v_mfma_f32_16x16x32_bf16 v[28:31], v[164:167], v[196:199], v[28:31]
	v_mfma_f32_16x16x32_bf16 v[24:27], v[172:175], v[196:199], v[24:27]
	v_mfma_f32_16x16x32_bf16 v[12:15], v[164:167], v[204:207], v[12:15]
	v_mfma_f32_16x16x32_bf16 v[8:11], v[172:175], v[204:207], v[8:11]
	v_mfma_f32_16x16x32_bf16 v[52:55], v[208:211], v[176:179], v[52:55]
	v_mfma_f32_16x16x32_bf16 v[48:51], v[216:219], v[176:179], v[48:51]
	v_mfma_f32_16x16x32_bf16 v[36:39], v[208:211], v[184:187], v[36:39]
	v_mfma_f32_16x16x32_bf16 v[32:35], v[216:219], v[184:187], v[32:35]
	v_mfma_f32_16x16x32_bf16 v[20:23], v[208:211], v[192:195], v[20:23]
	v_mfma_f32_16x16x32_bf16 v[16:19], v[216:219], v[192:195], v[16:19]
	v_mfma_f32_16x16x32_bf16 v[4:7], v[208:211], v[200:203], v[4:7]
	v_mfma_f32_16x16x32_bf16 v[0:3], v[216:219], v[200:203], v[0:3]
	v_mfma_f32_16x16x32_bf16 v[52:55], v[212:215], v[180:183], v[52:55]
	v_mfma_f32_16x16x32_bf16 v[48:51], v[220:223], v[180:183], v[48:51]
	v_mfma_f32_16x16x32_bf16 v[36:39], v[212:215], v[188:191], v[36:39]
	v_mfma_f32_16x16x32_bf16 v[32:35], v[220:223], v[188:191], v[32:35]
	v_mfma_f32_16x16x32_bf16 v[20:23], v[212:215], v[196:199], v[20:23]
	v_mfma_f32_16x16x32_bf16 v[16:19], v[220:223], v[196:199], v[16:19]
	v_mfma_f32_16x16x32_bf16 v[4:7], v[212:215], v[204:207], v[4:7]
	v_mfma_f32_16x16x32_bf16 v[0:3], v[220:223], v[204:207], v[0:3]
	s_add_i32 s20, 16, 0x18000
	v_add_u32_e32 v138, s20, v160
	s_barrier
	ds_read_b128 v[154:157], v138
	ds_read_b128 v[164:167], v138 offset:1024
	ds_read_b128 v[168:171], v138 offset:2048
	ds_read_b128 v[172:175], v138 offset:3072
	s_add_u32 s18, s18, 0x40000
	s_addc_u32 s19, s19, 0
	s_mov_b32 m0, s37
	v_lshl_add_u64 v[158:159], s[18:19], 0, v[144:145]
	ds_read_b128 v[176:179], v162 offset:32768
	ds_read_b128 v[180:183], v162 offset:33792
	ds_read_b128 v[184:187], v162 offset:34816
	ds_read_b128 v[188:191], v162 offset:35840
	ds_read_b128 v[192:195], v162 offset:36864
	ds_read_b128 v[196:199], v162 offset:37888
	ds_read_b128 v[200:203], v162 offset:38912
	ds_read_b128 v[204:207], v162 offset:39936
	global_load_lds_dwordx4 v[158:159], off
	v_lshl_add_u64 v[158:159], s[18:19], 0, v[146:147]
	s_mov_b32 m0, s46
	s_nop 0
	global_load_lds_dwordx4 v[158:159], off
	s_add_i32 s18, 16, 0x1c000
	v_add_u32_e32 v138, s18, v160
	ds_read_b128 v[208:211], v138
	ds_read_b128 v[212:215], v138 offset:1024
	ds_read_b128 v[216:219], v138 offset:2048
	ds_read_b128 v[220:223], v138 offset:3072
	s_waitcnt vmcnt(8) lgkmcnt(0)
	s_barrier
	v_mfma_f32_16x16x32_bf16 v[124:127], v[154:157], v[176:179], v[124:127]
	v_mfma_f32_16x16x32_bf16 v[120:123], v[168:171], v[176:179], v[120:123]
	v_mfma_f32_16x16x32_bf16 v[108:111], v[154:157], v[184:187], v[108:111]
	v_mfma_f32_16x16x32_bf16 v[104:107], v[168:171], v[184:187], v[104:107]
	v_mfma_f32_16x16x32_bf16 v[92:95], v[154:157], v[192:195], v[92:95]
	v_mfma_f32_16x16x32_bf16 v[88:91], v[168:171], v[192:195], v[88:91]
	v_mfma_f32_16x16x32_bf16 v[76:79], v[154:157], v[200:203], v[76:79]
	v_mfma_f32_16x16x32_bf16 v[72:75], v[168:171], v[200:203], v[72:75]
	v_mfma_f32_16x16x32_bf16 v[124:127], v[164:167], v[180:183], v[124:127]
	v_mfma_f32_16x16x32_bf16 v[120:123], v[172:175], v[180:183], v[120:123]
	v_mfma_f32_16x16x32_bf16 v[108:111], v[164:167], v[188:191], v[108:111]
	v_mfma_f32_16x16x32_bf16 v[104:107], v[172:175], v[188:191], v[104:107]
	v_mfma_f32_16x16x32_bf16 v[92:95], v[164:167], v[196:199], v[92:95]
	v_mfma_f32_16x16x32_bf16 v[88:91], v[172:175], v[196:199], v[88:91]
	v_mfma_f32_16x16x32_bf16 v[76:79], v[164:167], v[204:207], v[76:79]
	v_mfma_f32_16x16x32_bf16 v[72:75], v[172:175], v[204:207], v[72:75]
	v_mfma_f32_16x16x32_bf16 v[116:119], v[208:211], v[176:179], v[116:119]
	v_mfma_f32_16x16x32_bf16 v[112:115], v[216:219], v[176:179], v[112:115]
	v_mfma_f32_16x16x32_bf16 v[100:103], v[208:211], v[184:187], v[100:103]
	v_mfma_f32_16x16x32_bf16 v[96:99], v[216:219], v[184:187], v[96:99]
	v_mfma_f32_16x16x32_bf16 v[84:87], v[208:211], v[192:195], v[84:87]
	v_mfma_f32_16x16x32_bf16 v[80:83], v[216:219], v[192:195], v[80:83]
	v_mfma_f32_16x16x32_bf16 v[68:71], v[208:211], v[200:203], v[68:71]
	v_mfma_f32_16x16x32_bf16 v[64:67], v[216:219], v[200:203], v[64:67]
	v_mfma_f32_16x16x32_bf16 v[116:119], v[212:215], v[180:183], v[116:119]
	v_mfma_f32_16x16x32_bf16 v[112:115], v[220:223], v[180:183], v[112:115]
	v_mfma_f32_16x16x32_bf16 v[100:103], v[212:215], v[188:191], v[100:103]
	v_mfma_f32_16x16x32_bf16 v[96:99], v[220:223], v[188:191], v[96:99]
	v_mfma_f32_16x16x32_bf16 v[84:87], v[212:215], v[196:199], v[84:87]
	v_mfma_f32_16x16x32_bf16 v[80:83], v[220:223], v[196:199], v[80:83]
	v_mfma_f32_16x16x32_bf16 v[68:71], v[212:215], v[204:207], v[68:71]
	v_mfma_f32_16x16x32_bf16 v[64:67], v[220:223], v[204:207], v[64:67]
	s_barrier
	ds_read_b128 v[176:179], v162 offset:49152
	ds_read_b128 v[180:183], v162 offset:50176
	ds_read_b128 v[184:187], v162 offset:51200
	ds_read_b128 v[188:191], v162 offset:52224
	ds_read_b128 v[192:195], v162 offset:53248
	ds_read_b128 v[196:199], v162 offset:54272
	ds_read_b128 v[200:203], v162 offset:55296
	ds_read_b128 v[204:207], v162 offset:56320
	s_add_i32 s19, s20, s5
	v_lshl_add_u64 v[130:131], v[130:131], 0, s[28:29]
	s_mov_b32 m0, s19
	s_nop 0
	global_load_lds_dwordx4 v[130:131], off
	v_lshl_add_u64 v[130:131], v[132:133], 0, s[28:29]
	s_add_i32 m0, s19, 0x2000
	s_nop 0
	global_load_lds_dwordx4 v[130:131], off
	s_mov_b32 m0, s47
	v_lshl_add_u64 v[130:131], v[134:135], 0, s[28:29]
	global_load_lds_dwordx4 v[130:131], off
	v_lshl_add_u64 v[130:131], v[136:137], 0, s[28:29]
	s_mov_b32 m0, s92
	s_nop 0
	global_load_lds_dwordx4 v[130:131], off
	s_add_u32 s14, s14, 0x40080
	s_addc_u32 s15, s15, 0
	s_add_i32 s18, s18, s5
	v_lshl_add_u64 v[130:131], s[14:15], 0, v[128:129]
	s_mov_b32 m0, s18
	s_nop 0
	global_load_lds_dwordx4 v[130:131], off
	v_lshl_add_u64 v[130:131], s[14:15], 0, v[148:149]
	s_add_i32 m0, s18, 0x2000
	s_nop 0
	global_load_lds_dwordx4 v[130:131], off
	s_waitcnt vmcnt(8) lgkmcnt(0)
	s_barrier
	v_mfma_f32_16x16x32_bf16 v[60:63], v[154:157], v[176:179], v[60:63]
	v_mfma_f32_16x16x32_bf16 v[56:59], v[168:171], v[176:179], v[56:59]
	v_mfma_f32_16x16x32_bf16 v[44:47], v[154:157], v[184:187], v[44:47]
	v_mfma_f32_16x16x32_bf16 v[40:43], v[168:171], v[184:187], v[40:43]
	v_mfma_f32_16x16x32_bf16 v[28:31], v[154:157], v[192:195], v[28:31]
	v_mfma_f32_16x16x32_bf16 v[24:27], v[168:171], v[192:195], v[24:27]
	v_mfma_f32_16x16x32_bf16 v[12:15], v[154:157], v[200:203], v[12:15]
	v_mfma_f32_16x16x32_bf16 v[8:11], v[168:171], v[200:203], v[8:11]
	v_mfma_f32_16x16x32_bf16 v[60:63], v[164:167], v[180:183], v[60:63]
	v_mfma_f32_16x16x32_bf16 v[56:59], v[172:175], v[180:183], v[56:59]
	v_mfma_f32_16x16x32_bf16 v[44:47], v[164:167], v[188:191], v[44:47]
	v_mfma_f32_16x16x32_bf16 v[40:43], v[172:175], v[188:191], v[40:43]
	v_mfma_f32_16x16x32_bf16 v[28:31], v[164:167], v[196:199], v[28:31]
	v_mfma_f32_16x16x32_bf16 v[24:27], v[172:175], v[196:199], v[24:27]
	v_mfma_f32_16x16x32_bf16 v[12:15], v[164:167], v[204:207], v[12:15]
	v_mfma_f32_16x16x32_bf16 v[8:11], v[172:175], v[204:207], v[8:11]
	v_mfma_f32_16x16x32_bf16 v[52:55], v[208:211], v[176:179], v[52:55]
	v_mfma_f32_16x16x32_bf16 v[48:51], v[216:219], v[176:179], v[48:51]
	v_mfma_f32_16x16x32_bf16 v[36:39], v[208:211], v[184:187], v[36:39]
	v_mfma_f32_16x16x32_bf16 v[32:35], v[216:219], v[184:187], v[32:35]
	v_mfma_f32_16x16x32_bf16 v[20:23], v[208:211], v[192:195], v[20:23]
	v_mfma_f32_16x16x32_bf16 v[16:19], v[216:219], v[192:195], v[16:19]
	v_mfma_f32_16x16x32_bf16 v[4:7], v[208:211], v[200:203], v[4:7]
	v_mfma_f32_16x16x32_bf16 v[0:3], v[216:219], v[200:203], v[0:3]
	v_mfma_f32_16x16x32_bf16 v[52:55], v[212:215], v[180:183], v[52:55]
	v_mfma_f32_16x16x32_bf16 v[48:51], v[220:223], v[180:183], v[48:51]
	v_mfma_f32_16x16x32_bf16 v[36:39], v[212:215], v[188:191], v[36:39]
	v_mfma_f32_16x16x32_bf16 v[32:35], v[220:223], v[188:191], v[32:35]
	v_mfma_f32_16x16x32_bf16 v[20:23], v[212:215], v[196:199], v[20:23]
	v_mfma_f32_16x16x32_bf16 v[16:19], v[220:223], v[196:199], v[16:19]
	v_mfma_f32_16x16x32_bf16 v[4:7], v[212:215], v[204:207], v[4:7]
	v_mfma_f32_16x16x32_bf16 v[0:3], v[220:223], v[204:207], v[0:3]
	s_add_i32 s34, s34, 2
	s_add_u32 vcc_lo, vcc_lo, 0x100
	s_addc_u32 vcc_hi, vcc_hi, 0
	s_add_u32 s25, s25, 0x100
	s_addc_u32 s31, s31, 0
	s_cmp_gt_u32 s34, 13
	s_cbranch_scc1 .Lgout_exit
	s_barrier
	s_branch .LBB0_128

.Lgout_epi:
	s_setprio 0
	s_nop 0
	s_nop 0
	s_nop 0
	s_nop 0
	s_nop 0
	s_nop 0
	s_cmp_lt_i32 s8, 0
	s_cselect_b64 s[14:15], -1, 0
	s_cmp_gt_i32 s8, -1
	s_cbranch_scc1 .LBB0_131
	v_mul_f32_e32 v131, 0x3d372713, v120
	v_mul_f32_e32 v131, v120, v131
	v_fma_f32 v131, v120, v131, v120
	v_mul_f32_e32 v131, 0x3fcc422a, v131
	v_mul_f32_e32 v131, 0xbfb8aa3b, v131
	v_exp_f32_e32 v131, v131
	v_mul_f32_e32 v130, 0x3d372713, v124
	v_mul_f32_e32 v130, v124, v130
	v_fma_f32 v130, v124, v130, v124
	v_add_f32_e32 v131, 1.0, v131
	v_rcp_f32_e32 v132, v131
	v_mul_f32_e32 v131, 0x3d372713, v125
	v_mul_f32_e32 v131, v125, v131
	v_fma_f32 v131, v125, v131, v125
	v_mul_f32_e32 v130, 0x3fcc422a, v130
	v_mul_f32_e32 v131, 0x3fcc422a, v131
	v_mul_f32_e32 v130, 0xbfb8aa3b, v130
	v_mul_f32_e32 v131, 0xbfb8aa3b, v131
	v_mul_f32_e32 v135, 0x3d372713, v122
	v_exp_f32_e32 v130, v130
	v_exp_f32_e32 v131, v131
	v_mul_f32_e32 v135, v122, v135
	v_fma_f32 v135, v122, v135, v122
	v_mul_f32_e32 v135, 0x3fcc422a, v135
	v_mul_f32_e32 v135, 0xbfb8aa3b, v135
	v_add_f32_e32 v130, 1.0, v130
	v_add_f32_e32 v131, 1.0, v131
	v_exp_f32_e32 v135, v135
	v_rcp_f32_e32 v130, v130
	v_rcp_f32_e32 v131, v131
	v_mul_f32_e32 v133, 0x3d372713, v121
	v_add_f32_e32 v135, 1.0, v135
	v_mul_f32_e32 v134, 0x3d372713, v126
	v_rcp_f32_e32 v136, v135
	v_mul_f32_e32 v135, 0x3d372713, v127
	v_pk_mul_f32 v[124:125], v[124:125], v[130:131]
	v_mul_f32_e32 v130, 0x3d372713, v123
	v_mul_f32_e32 v133, v121, v133
	v_mul_f32_e32 v134, v126, v134
	v_mul_f32_e32 v135, v127, v135
	v_mul_f32_e32 v130, v123, v130
	v_fma_f32 v133, v121, v133, v121
	v_fma_f32 v134, v126, v134, v126
	v_fma_f32 v135, v127, v135, v127
	v_fma_f32 v130, v123, v130, v123
	v_mul_f32_e32 v133, 0x3fcc422a, v133
	v_mul_f32_e32 v134, 0x3fcc422a, v134
	v_mul_f32_e32 v135, 0x3fcc422a, v135
	v_mul_f32_e32 v130, 0x3fcc422a, v130
	v_mul_f32_e32 v133, 0xbfb8aa3b, v133
	v_mul_f32_e32 v134, 0xbfb8aa3b, v134
	v_mul_f32_e32 v135, 0xbfb8aa3b, v135
	v_mul_f32_e32 v130, 0xbfb8aa3b, v130
	v_exp_f32_e32 v133, v133
	v_exp_f32_e32 v134, v134
	v_exp_f32_e32 v135, v135
	v_exp_f32_e32 v130, v130
	v_add_f32_e32 v133, 1.0, v133
	v_add_f32_e32 v134, 1.0, v134
	v_add_f32_e32 v135, 1.0, v135
	v_add_f32_e32 v130, 1.0, v130
	v_rcp_f32_e32 v133, v133
	v_rcp_f32_e32 v134, v134
	v_rcp_f32_e32 v135, v135
	v_rcp_f32_e32 v137, v130
	v_pk_mul_f32 v[120:121], v[120:121], v[132:133]
	v_pk_mul_f32 v[126:127], v[126:127], v[134:135]
	v_pk_mul_f32 v[122:123], v[122:123], v[136:137]

.LBB0_270:
	v_lshl_add_u32 v154, s14, 8, v143
	v_readlane_b32 s14, v252, 43
	v_mov_b64_e32 v[0:1], 0x600
	v_ashrrev_i32_e32 v155, 31, v154
	v_readlane_b32 s15, v252, 44
	v_cmp_lt_i64_e32 vcc, s[34:35], v[0:1]
	s_ashr_i32 s13, s12, 31
	v_lshl_add_u64 v[0:1], v[154:155], 2, s[14:15]
	global_load_dword v156, v[0:1], off
	global_load_dword v171, v[0:1], off offset:64
	global_load_dword v170, v[0:1], off offset:128
	global_load_dword v169, v[0:1], off offset:192
	global_load_dword v168, v[0:1], off offset:512
	global_load_dword v167, v[0:1], off offset:576
	global_load_dword v166, v[0:1], off offset:640
	global_load_dword v165, v[0:1], off offset:704
	s_lshl_b64 s[0:1], s[12:13], 19
	v_readlane_b32 s24, v252, 55
	v_readlane_b32 s25, v252, 56
	s_add_u32 s42, s24, s0
	s_addc_u32 s43, s25, s1
	s_and_b64 s[0:1], vcc, exec
	s_cselect_b32 s0, s43, s31
	s_cselect_b32 s1, s42, s30
	s_ashr_i32 s9, s8, 31
	s_lshl_b64 s[24:25], s[8:9], 19
	v_readlane_b32 s34, v252, 41
	v_readlane_b32 s35, v252, 42
	s_add_u32 s44, s34, s24
	s_addc_u32 s45, s35, s25
	s_and_b64 s[24:25], vcc, exec
	s_cselect_b32 s9, s45, s19
	s_cselect_b32 s13, s44, s18
	s_add_u32 s30, s30, 0x40080
	s_addc_u32 s31, s31, 0
	s_add_u32 s17, s18, 0x100
	v_mov_b32_e32 v0, 0
	s_addc_u32 s24, s19, 0
	s_mov_b32 s25, -2
	v_mov_b32_e32 v1, v0
	v_mov_b32_e32 v2, v0
	v_mov_b32_e32 v3, v0
	v_mov_b32_e32 v4, v0
	v_mov_b32_e32 v5, v0
	v_mov_b32_e32 v6, v0
	v_mov_b32_e32 v7, v0
	v_mov_b32_e32 v16, v0
	v_mov_b32_e32 v17, v0
	v_mov_b32_e32 v18, v0
	v_mov_b32_e32 v19, v0
	v_mov_b32_e32 v20, v0
	v_mov_b32_e32 v21, v0
	v_mov_b32_e32 v22, v0
	v_mov_b32_e32 v23, v0
	v_mov_b32_e32 v32, v0
	v_mov_b32_e32 v33, v0
	v_mov_b32_e32 v34, v0
	v_mov_b32_e32 v35, v0
	v_mov_b32_e32 v36, v0
	v_mov_b32_e32 v37, v0
	v_mov_b32_e32 v38, v0
	v_mov_b32_e32 v39, v0
	v_mov_b32_e32 v48, v0
	v_mov_b32_e32 v49, v0
	v_mov_b32_e32 v50, v0
	v_mov_b32_e32 v51, v0
	v_mov_b32_e32 v52, v0
	v_mov_b32_e32 v53, v0
	v_mov_b32_e32 v54, v0
	v_mov_b32_e32 v55, v0
	v_mov_b32_e32 v8, v0
	v_mov_b32_e32 v9, v0
	v_mov_b32_e32 v10, v0
	v_mov_b32_e32 v11, v0
	v_mov_b32_e32 v12, v0
	v_mov_b32_e32 v13, v0
	v_mov_b32_e32 v14, v0
	v_mov_b32_e32 v15, v0
	v_mov_b32_e32 v24, v0
	v_mov_b32_e32 v25, v0
	v_mov_b32_e32 v26, v0
	v_mov_b32_e32 v27, v0
	v_mov_b32_e32 v28, v0
	v_mov_b32_e32 v29, v0
	v_mov_b32_e32 v30, v0
	v_mov_b32_e32 v31, v0
	v_mov_b32_e32 v40, v0
	v_mov_b32_e32 v41, v0
	v_mov_b32_e32 v42, v0
	v_mov_b32_e32 v43, v0
	v_mov_b32_e32 v44, v0
	v_mov_b32_e32 v45, v0
	v_mov_b32_e32 v46, v0
	v_mov_b32_e32 v47, v0
	v_mov_b32_e32 v56, v0
	v_mov_b32_e32 v57, v0
	v_mov_b32_e32 v58, v0
	v_mov_b32_e32 v59, v0
	v_mov_b32_e32 v60, v0
	v_mov_b32_e32 v61, v0
	v_mov_b32_e32 v62, v0
	v_mov_b32_e32 v63, v0
	v_mov_b32_e32 v64, v0
	v_mov_b32_e32 v65, v0
	v_mov_b32_e32 v66, v0
	v_mov_b32_e32 v67, v0
	v_mov_b32_e32 v68, v0
	v_mov_b32_e32 v69, v0
	v_mov_b32_e32 v70, v0
	v_mov_b32_e32 v71, v0
	v_mov_b32_e32 v80, v0
	v_mov_b32_e32 v81, v0
	v_mov_b32_e32 v82, v0
	v_mov_b32_e32 v83, v0
	v_mov_b32_e32 v84, v0
	v_mov_b32_e32 v85, v0
	v_mov_b32_e32 v86, v0
	v_mov_b32_e32 v87, v0
	v_mov_b32_e32 v96, v0
	v_mov_b32_e32 v97, v0
	v_mov_b32_e32 v98, v0
	v_mov_b32_e32 v99, v0
	v_mov_b32_e32 v100, v0
	v_mov_b32_e32 v101, v0
	v_mov_b32_e32 v102, v0
	v_mov_b32_e32 v103, v0
	v_mov_b32_e32 v112, v0
	v_mov_b32_e32 v113, v0
	v_mov_b32_e32 v114, v0
	v_mov_b32_e32 v115, v0
	v_mov_b32_e32 v116, v0
	v_mov_b32_e32 v117, v0
	v_mov_b32_e32 v118, v0
	v_mov_b32_e32 v119, v0
	v_mov_b32_e32 v72, v0
	v_mov_b32_e32 v73, v0
	v_mov_b32_e32 v74, v0
	v_mov_b32_e32 v75, v0
	v_mov_b32_e32 v76, v0
	v_mov_b32_e32 v77, v0
	v_mov_b32_e32 v78, v0
	v_mov_b32_e32 v79, v0
	v_mov_b32_e32 v88, v0
	v_mov_b32_e32 v89, v0
	v_mov_b32_e32 v90, v0
	v_mov_b32_e32 v91, v0
	v_mov_b32_e32 v92, v0
	v_mov_b32_e32 v93, v0
	v_mov_b32_e32 v94, v0
	v_mov_b32_e32 v95, v0
	v_mov_b32_e32 v104, v0
	v_mov_b32_e32 v105, v0
	v_mov_b32_e32 v106, v0
	v_mov_b32_e32 v107, v0
	v_mov_b32_e32 v108, v0
	v_mov_b32_e32 v109, v0
	v_mov_b32_e32 v110, v0
	v_mov_b32_e32 v111, v0
	v_mov_b32_e32 v120, v0
	v_mov_b32_e32 v121, v0
	v_mov_b32_e32 v122, v0
	v_mov_b32_e32 v123, v0
	v_mov_b32_e32 v124, v0
	v_mov_b32_e32 v125, v0
	v_mov_b32_e32 v126, v0
	v_mov_b32_e32 v127, v0
	s_cmpk_gt_u32 s48, 0xff
	s_cbranch_scc0 .Lgin_enter
	s_barrier
	s_setprio 1
.Lgin_enter:
.LBB0_271:
	s_add_u32 s14, s30, 0xfffc0080
	s_addc_u32 s15, s31, -1
	s_add_i32 s20, 16, 0x10000
	v_add_u32_e32 v130, s20, v162
	ds_read_b128 v[158:161], v130
	ds_read_b128 v[172:175], v130 offset:1024
	ds_read_b128 v[176:179], v130 offset:2048
	ds_read_b128 v[180:183], v130 offset:3072
	s_cmp_eq_u32 s25, 12
	s_cselect_b32 s19, s0, s15
	s_cselect_b32 s18, s1, s14
	s_cselect_b32 s15, s9, s24
	s_cselect_b32 s14, s13, s17
	v_lshl_add_u64 v[130:131], s[30:31], 0, v[150:151]
	s_add_i32 m0, s5, 0xc000
	ds_read_b128 v[184:187], v164
	ds_read_b128 v[188:191], v164 offset:1024
	ds_read_b128 v[192:195], v164 offset:2048
	ds_read_b128 v[196:199], v164 offset:3072
	ds_read_b128 v[200:203], v164 offset:4096
	ds_read_b128 v[204:207], v164 offset:5120
	ds_read_b128 v[208:211], v164 offset:6144
	ds_read_b128 v[212:215], v164 offset:7168
	global_load_lds_dwordx4 v[130:131], off
	v_lshl_add_u64 v[130:131], s[30:31], 0, v[152:153]
	s_add_i32 m0, s5, 0xe000
	s_nop 0
	global_load_lds_dwordx4 v[130:131], off
	s_add_i32 s41, 16, 0x14000
	v_add_u32_e32 v130, s41, v162
	ds_read_b128 v[216:219], v130
	ds_read_b128 v[220:223], v130 offset:1024
	ds_read_b128 v[224:227], v130 offset:2048
	ds_read_b128 v[228:231], v130 offset:3072
	s_waitcnt vmcnt(8) lgkmcnt(0)
	s_barrier
	v_mfma_f32_16x16x32_bf16 v[124:127], v[158:161], v[184:187], v[124:127]
	v_mfma_f32_16x16x32_bf16 v[120:123], v[176:179], v[184:187], v[120:123]
	v_mfma_f32_16x16x32_bf16 v[108:111], v[158:161], v[192:195], v[108:111]
	v_mfma_f32_16x16x32_bf16 v[104:107], v[176:179], v[192:195], v[104:107]
	v_mfma_f32_16x16x32_bf16 v[92:95], v[158:161], v[200:203], v[92:95]
	v_mfma_f32_16x16x32_bf16 v[88:91], v[176:179], v[200:203], v[88:91]
	v_mfma_f32_16x16x32_bf16 v[76:79], v[158:161], v[208:211], v[76:79]
	v_mfma_f32_16x16x32_bf16 v[72:75], v[176:179], v[208:211], v[72:75]
	v_mfma_f32_16x16x32_bf16 v[124:127], v[172:175], v[188:191], v[124:127]
	v_mfma_f32_16x16x32_bf16 v[120:123], v[180:183], v[188:191], v[120:123]
	v_mfma_f32_16x16x32_bf16 v[108:111], v[172:175], v[196:199], v[108:111]
	v_mfma_f32_16x16x32_bf16 v[104:107], v[180:183], v[196:199], v[104:107]
	v_mfma_f32_16x16x32_bf16 v[92:95], v[172:175], v[204:207], v[92:95]
	v_mfma_f32_16x16x32_bf16 v[88:91], v[180:183], v[204:207], v[88:91]
	v_mfma_f32_16x16x32_bf16 v[76:79], v[172:175], v[212:215], v[76:79]
	v_mfma_f32_16x16x32_bf16 v[72:75], v[180:183], v[212:215], v[72:75]
	v_mfma_f32_16x16x32_bf16 v[116:119], v[216:219], v[184:187], v[116:119]
	v_mfma_f32_16x16x32_bf16 v[112:115], v[224:227], v[184:187], v[112:115]
	v_mfma_f32_16x16x32_bf16 v[100:103], v[216:219], v[192:195], v[100:103]
	v_mfma_f32_16x16x32_bf16 v[96:99], v[224:227], v[192:195], v[96:99]
	v_mfma_f32_16x16x32_bf16 v[84:87], v[216:219], v[200:203], v[84:87]
	v_mfma_f32_16x16x32_bf16 v[80:83], v[224:227], v[200:203], v[80:83]
	v_mfma_f32_16x16x32_bf16 v[68:71], v[216:219], v[208:211], v[68:71]
	v_mfma_f32_16x16x32_bf16 v[64:67], v[224:227], v[208:211], v[64:67]
	v_mfma_f32_16x16x32_bf16 v[116:119], v[220:223], v[188:191], v[116:119]
	v_mfma_f32_16x16x32_bf16 v[112:115], v[228:231], v[188:191], v[112:115]
	v_mfma_f32_16x16x32_bf16 v[100:103], v[220:223], v[196:199], v[100:103]
	v_mfma_f32_16x16x32_bf16 v[96:99], v[228:231], v[196:199], v[96:99]
	v_mfma_f32_16x16x32_bf16 v[84:87], v[220:223], v[204:207], v[84:87]
	v_mfma_f32_16x16x32_bf16 v[80:83], v[228:231], v[204:207], v[80:83]
	v_mfma_f32_16x16x32_bf16 v[68:71], v[220:223], v[212:215], v[68:71]
	v_mfma_f32_16x16x32_bf16 v[64:67], v[228:231], v[212:215], v[64:67]
	s_barrier
	ds_read_b128 v[184:187], v164 offset:16384
	ds_read_b128 v[188:191], v164 offset:17408
	ds_read_b128 v[192:195], v164 offset:18432
	ds_read_b128 v[196:199], v164 offset:19456
	ds_read_b128 v[200:203], v164 offset:20480
	ds_read_b128 v[204:207], v164 offset:21504
	ds_read_b128 v[208:211], v164 offset:22528
	ds_read_b128 v[212:215], v164 offset:23552
	s_add_i32 s20, s20, s92
	v_lshl_add_u64 v[130:131], s[14:15], 0, v[128:129]
	s_mov_b32 m0, s20
	v_lshl_add_u64 v[132:133], s[14:15], 0, v[148:149]
	global_load_lds_dwordx4 v[130:131], off
	s_add_i32 m0, s20, 0x2000
	s_nop 0
	global_load_lds_dwordx4 v[132:133], off
	s_mov_b32 m0, s5
	v_lshl_add_u64 v[134:135], s[18:19], 0, v[144:145]
	global_load_lds_dwordx4 v[134:135], off
	v_lshl_add_u64 v[136:137], s[18:19], 0, v[146:147]
	s_mov_b32 m0, s4
	s_nop 0
	global_load_lds_dwordx4 v[136:137], off
	s_add_u32 s34, s14, 0x40000
	s_addc_u32 s35, s15, 0
	s_add_i32 s20, s41, s92
	v_lshl_add_u64 v[138:139], s[34:35], 0, v[128:129]
	s_mov_b32 m0, s20
	s_nop 0
	global_load_lds_dwordx4 v[138:139], off
	v_lshl_add_u64 v[138:139], s[34:35], 0, v[148:149]
	s_add_i32 m0, s20, 0x2000
	s_nop 0
	global_load_lds_dwordx4 v[138:139], off
	s_waitcnt vmcnt(8) lgkmcnt(0)
	s_barrier
	v_mfma_f32_16x16x32_bf16 v[60:63], v[158:161], v[184:187], v[60:63]
	v_mfma_f32_16x16x32_bf16 v[56:59], v[176:179], v[184:187], v[56:59]
	v_mfma_f32_16x16x32_bf16 v[44:47], v[158:161], v[192:195], v[44:47]
	v_mfma_f32_16x16x32_bf16 v[40:43], v[176:179], v[192:195], v[40:43]
	v_mfma_f32_16x16x32_bf16 v[28:31], v[158:161], v[200:203], v[28:31]
	v_mfma_f32_16x16x32_bf16 v[24:27], v[176:179], v[200:203], v[24:27]
	v_mfma_f32_16x16x32_bf16 v[12:15], v[158:161], v[208:211], v[12:15]
	v_mfma_f32_16x16x32_bf16 v[8:11], v[176:179], v[208:211], v[8:11]
	v_mfma_f32_16x16x32_bf16 v[60:63], v[172:175], v[188:191], v[60:63]
	v_mfma_f32_16x16x32_bf16 v[56:59], v[180:183], v[188:191], v[56:59]
	v_mfma_f32_16x16x32_bf16 v[44:47], v[172:175], v[196:199], v[44:47]
	v_mfma_f32_16x16x32_bf16 v[40:43], v[180:183], v[196:199], v[40:43]
	v_mfma_f32_16x16x32_bf16 v[28:31], v[172:175], v[204:207], v[28:31]
	v_mfma_f32_16x16x32_bf16 v[24:27], v[180:183], v[204:207], v[24:27]
	v_mfma_f32_16x16x32_bf16 v[12:15], v[172:175], v[212:215], v[12:15]
	v_mfma_f32_16x16x32_bf16 v[8:11], v[180:183], v[212:215], v[8:11]
	v_mfma_f32_16x16x32_bf16 v[52:55], v[216:219], v[184:187], v[52:55]
	v_mfma_f32_16x16x32_bf16 v[48:51], v[224:227], v[184:187], v[48:51]
	v_mfma_f32_16x16x32_bf16 v[36:39], v[216:219], v[192:195], v[36:39]
	v_mfma_f32_16x16x32_bf16 v[32:35], v[224:227], v[192:195], v[32:35]
	v_mfma_f32_16x16x32_bf16 v[20:23], v[216:219], v[200:203], v[20:23]
	v_mfma_f32_16x16x32_bf16 v[16:19], v[224:227], v[200:203], v[16:19]
	v_mfma_f32_16x16x32_bf16 v[4:7], v[216:219], v[208:211], v[4:7]
	v_mfma_f32_16x16x32_bf16 v[0:3], v[224:227], v[208:211], v[0:3]
	v_mfma_f32_16x16x32_bf16 v[52:55], v[220:223], v[188:191], v[52:55]
	v_mfma_f32_16x16x32_bf16 v[48:51], v[228:231], v[188:191], v[48:51]
	v_mfma_f32_16x16x32_bf16 v[36:39], v[220:223], v[196:199], v[36:39]
	v_mfma_f32_16x16x32_bf16 v[32:35], v[228:231], v[196:199], v[32:35]
	v_mfma_f32_16x16x32_bf16 v[20:23], v[220:223], v[204:207], v[20:23]
	v_mfma_f32_16x16x32_bf16 v[16:19], v[228:231], v[204:207], v[16:19]
	v_mfma_f32_16x16x32_bf16 v[4:7], v[220:223], v[212:215], v[4:7]
	v_mfma_f32_16x16x32_bf16 v[0:3], v[228:231], v[212:215], v[0:3]
	s_add_i32 s20, 16, 0x18000
	v_add_u32_e32 v138, s20, v162
	s_barrier
	ds_read_b128 v[158:161], v138
	ds_read_b128 v[172:175], v138 offset:1024
	ds_read_b128 v[176:179], v138 offset:2048
	ds_read_b128 v[180:183], v138 offset:3072
	s_add_u32 s18, s18, 0x40000
	s_addc_u32 s19, s19, 0
	s_mov_b32 m0, s36
	v_lshl_add_u64 v[216:217], s[18:19], 0, v[144:145]
	ds_read_b128 v[184:187], v164 offset:32768
	ds_read_b128 v[188:191], v164 offset:33792
	ds_read_b128 v[192:195], v164 offset:34816
	ds_read_b128 v[196:199], v164 offset:35840
	ds_read_b128 v[200:203], v164 offset:36864
	ds_read_b128 v[204:207], v164 offset:37888
	ds_read_b128 v[208:211], v164 offset:38912
	ds_read_b128 v[212:215], v164 offset:39936
	global_load_lds_dwordx4 v[216:217], off
	v_lshl_add_u64 v[216:217], s[18:19], 0, v[146:147]
	s_mov_b32 m0, s37
	s_nop 0
	global_load_lds_dwordx4 v[216:217], off
	s_add_i32 s18, 16, 0x1c000
	v_add_u32_e32 v138, s18, v162
	ds_read_b128 v[216:219], v138
	ds_read_b128 v[220:223], v138 offset:1024
	ds_read_b128 v[224:227], v138 offset:2048
	ds_read_b128 v[228:231], v138 offset:3072
	s_waitcnt vmcnt(8) lgkmcnt(0)
	s_barrier
	v_mfma_f32_16x16x32_bf16 v[124:127], v[158:161], v[184:187], v[124:127]
	v_mfma_f32_16x16x32_bf16 v[120:123], v[176:179], v[184:187], v[120:123]
	v_mfma_f32_16x16x32_bf16 v[108:111], v[158:161], v[192:195], v[108:111]
	v_mfma_f32_16x16x32_bf16 v[104:107], v[176:179], v[192:195], v[104:107]
	v_mfma_f32_16x16x32_bf16 v[92:95], v[158:161], v[200:203], v[92:95]
	v_mfma_f32_16x16x32_bf16 v[88:91], v[176:179], v[200:203], v[88:91]
	v_mfma_f32_16x16x32_bf16 v[76:79], v[158:161], v[208:211], v[76:79]
	v_mfma_f32_16x16x32_bf16 v[72:75], v[176:179], v[208:211], v[72:75]
	v_mfma_f32_16x16x32_bf16 v[124:127], v[172:175], v[188:191], v[124:127]
	v_mfma_f32_16x16x32_bf16 v[120:123], v[180:183], v[188:191], v[120:123]
	v_mfma_f32_16x16x32_bf16 v[108:111], v[172:175], v[196:199], v[108:111]
	v_mfma_f32_16x16x32_bf16 v[104:107], v[180:183], v[196:199], v[104:107]
	v_mfma_f32_16x16x32_bf16 v[92:95], v[172:175], v[204:207], v[92:95]
	v_mfma_f32_16x16x32_bf16 v[88:91], v[180:183], v[204:207], v[88:91]
	v_mfma_f32_16x16x32_bf16 v[76:79], v[172:175], v[212:215], v[76:79]
	v_mfma_f32_16x16x32_bf16 v[72:75], v[180:183], v[212:215], v[72:75]
	v_mfma_f32_16x16x32_bf16 v[116:119], v[216:219], v[184:187], v[116:119]
	v_mfma_f32_16x16x32_bf16 v[112:115], v[224:227], v[184:187], v[112:115]
	v_mfma_f32_16x16x32_bf16 v[100:103], v[216:219], v[192:195], v[100:103]
	v_mfma_f32_16x16x32_bf16 v[96:99], v[224:227], v[192:195], v[96:99]
	v_mfma_f32_16x16x32_bf16 v[84:87], v[216:219], v[200:203], v[84:87]
	v_mfma_f32_16x16x32_bf16 v[80:83], v[224:227], v[200:203], v[80:83]
	v_mfma_f32_16x16x32_bf16 v[68:71], v[216:219], v[208:211], v[68:71]
	v_mfma_f32_16x16x32_bf16 v[64:67], v[224:227], v[208:211], v[64:67]
	v_mfma_f32_16x16x32_bf16 v[116:119], v[220:223], v[188:191], v[116:119]
	v_mfma_f32_16x16x32_bf16 v[112:115], v[228:231], v[188:191], v[112:115]
	v_mfma_f32_16x16x32_bf16 v[100:103], v[220:223], v[196:199], v[100:103]
	v_mfma_f32_16x16x32_bf16 v[96:99], v[228:231], v[196:199], v[96:99]
	v_mfma_f32_16x16x32_bf16 v[84:87], v[220:223], v[204:207], v[84:87]
	v_mfma_f32_16x16x32_bf16 v[80:83], v[228:231], v[204:207], v[80:83]
	v_mfma_f32_16x16x32_bf16 v[68:71], v[220:223], v[212:215], v[68:71]
	v_mfma_f32_16x16x32_bf16 v[64:67], v[228:231], v[212:215], v[64:67]
	s_barrier
	ds_read_b128 v[184:187], v164 offset:49152
	ds_read_b128 v[188:191], v164 offset:50176
	ds_read_b128 v[192:195], v164 offset:51200
	ds_read_b128 v[196:199], v164 offset:52224
	ds_read_b128 v[200:203], v164 offset:53248
	ds_read_b128 v[204:207], v164 offset:54272
	ds_read_b128 v[208:211], v164 offset:55296
	ds_read_b128 v[212:215], v164 offset:56320
	s_add_i32 s19, s20, s92
	v_lshl_add_u64 v[130:131], v[130:131], 0, s[28:29]
	s_mov_b32 m0, s19
	s_nop 0
	global_load_lds_dwordx4 v[130:131], off
	v_lshl_add_u64 v[130:131], v[132:133], 0, s[28:29]
	s_add_i32 m0, s19, 0x2000
	s_nop 0
	global_load_lds_dwordx4 v[130:131], off
	s_mov_b32 m0, s46
	v_lshl_add_u64 v[130:131], v[134:135], 0, s[28:29]
	global_load_lds_dwordx4 v[130:131], off
	v_lshl_add_u64 v[130:131], v[136:137], 0, s[28:29]
	s_mov_b32 m0, s47
	s_nop 0
	global_load_lds_dwordx4 v[130:131], off
	s_add_u32 s14, s14, 0x40080
	s_addc_u32 s15, s15, 0
	s_add_i32 s18, s18, s92
	v_lshl_add_u64 v[130:131], s[14:15], 0, v[128:129]
	s_mov_b32 m0, s18
	s_nop 0
	global_load_lds_dwordx4 v[130:131], off
	v_lshl_add_u64 v[130:131], s[14:15], 0, v[148:149]
	s_add_i32 m0, s18, 0x2000
	s_nop 0
	global_load_lds_dwordx4 v[130:131], off
	s_waitcnt vmcnt(8) lgkmcnt(0)
	s_barrier
	v_mfma_f32_16x16x32_bf16 v[60:63], v[158:161], v[184:187], v[60:63]
	v_mfma_f32_16x16x32_bf16 v[56:59], v[176:179], v[184:187], v[56:59]
	v_mfma_f32_16x16x32_bf16 v[44:47], v[158:161], v[192:195], v[44:47]
	v_mfma_f32_16x16x32_bf16 v[40:43], v[176:179], v[192:195], v[40:43]
	v_mfma_f32_16x16x32_bf16 v[28:31], v[158:161], v[200:203], v[28:31]
	v_mfma_f32_16x16x32_bf16 v[24:27], v[176:179], v[200:203], v[24:27]
	v_mfma_f32_16x16x32_bf16 v[12:15], v[158:161], v[208:211], v[12:15]
	v_mfma_f32_16x16x32_bf16 v[8:11], v[176:179], v[208:211], v[8:11]
	v_mfma_f32_16x16x32_bf16 v[60:63], v[172:175], v[188:191], v[60:63]
	v_mfma_f32_16x16x32_bf16 v[56:59], v[180:183], v[188:191], v[56:59]
	v_mfma_f32_16x16x32_bf16 v[44:47], v[172:175], v[196:199], v[44:47]
	v_mfma_f32_16x16x32_bf16 v[40:43], v[180:183], v[196:199], v[40:43]
	v_mfma_f32_16x16x32_bf16 v[28:31], v[172:175], v[204:207], v[28:31]
	v_mfma_f32_16x16x32_bf16 v[24:27], v[180:183], v[204:207], v[24:27]
	v_mfma_f32_16x16x32_bf16 v[12:15], v[172:175], v[212:215], v[12:15]
	v_mfma_f32_16x16x32_bf16 v[8:11], v[180:183], v[212:215], v[8:11]
	v_mfma_f32_16x16x32_bf16 v[52:55], v[216:219], v[184:187], v[52:55]
	v_mfma_f32_16x16x32_bf16 v[48:51], v[224:227], v[184:187], v[48:51]
	v_mfma_f32_16x16x32_bf16 v[36:39], v[216:219], v[192:195], v[36:39]
	v_mfma_f32_16x16x32_bf16 v[32:35], v[224:227], v[192:195], v[32:35]
	v_mfma_f32_16x16x32_bf16 v[20:23], v[216:219], v[200:203], v[20:23]
	v_mfma_f32_16x16x32_bf16 v[16:19], v[224:227], v[200:203], v[16:19]
	v_mfma_f32_16x16x32_bf16 v[4:7], v[216:219], v[208:211], v[4:7]
	v_mfma_f32_16x16x32_bf16 v[0:3], v[224:227], v[208:211], v[0:3]
	v_mfma_f32_16x16x32_bf16 v[52:55], v[220:223], v[188:191], v[52:55]
	v_mfma_f32_16x16x32_bf16 v[48:51], v[228:231], v[188:191], v[48:51]
	v_mfma_f32_16x16x32_bf16 v[36:39], v[220:223], v[196:199], v[36:39]
	v_mfma_f32_16x16x32_bf16 v[32:35], v[228:231], v[196:199], v[32:35]
	v_mfma_f32_16x16x32_bf16 v[20:23], v[220:223], v[204:207], v[20:23]
	v_mfma_f32_16x16x32_bf16 v[16:19], v[228:231], v[204:207], v[16:19]
	v_mfma_f32_16x16x32_bf16 v[4:7], v[220:223], v[212:215], v[4:7]
	v_mfma_f32_16x16x32_bf16 v[0:3], v[228:231], v[212:215], v[0:3]
	s_add_i32 s25, s25, 2
	s_add_u32 s30, s30, 0x100
	s_addc_u32 s31, s31, 0
	s_add_u32 s17, s17, 0x100
	s_addc_u32 s24, s24, 0
	s_cmp_gt_u32 s25, 13
	s_cbranch_scc1 .Lgin_exit
	s_barrier
	s_branch .LBB0_271

.Lgin_epi:
	s_setprio 0
	s_nop 0
	s_nop 0
	s_nop 0
	s_nop 0
	s_nop 0
	s_nop 0
	s_waitcnt vmcnt(0)
	v_fmamk_f32 v130, v156, 0x3a800000, v235
	v_mul_f32_e32 v131, 0x4b800000, v130
	v_cmp_gt_f32_e32 vcc, s86, v130
	s_cmp_lt_i32 s40, 4
	s_cselect_b64 s[14:15], -1, 0
	v_cndmask_b32_e32 v130, v130, v131, vcc
	v_rsq_f32_e32 v130, v130
	s_cmp_gt_i32 s40, 3
	v_mul_f32_e32 v131, 0x45800000, v130
	v_cndmask_b32_e32 v156, v130, v131, vcc
	v_pk_mul_f32 v[126:127], v[156:157], v[126:127] op_sel_hi:[0,1]
	v_pk_mul_f32 v[124:125], v[156:157], v[124:125] op_sel_hi:[0,1]
	v_pk_mul_f32 v[158:159], v[156:157], v[122:123] op_sel_hi:[0,1]
	v_pk_mul_f32 v[160:161], v[156:157], v[120:121] op_sel_hi:[0,1]
	s_cbranch_scc1 .LBB0_274
	v_mul_f32_e32 v121, 0x3d372713, v160
	v_mul_f32_e32 v121, v160, v121
	v_fma_f32 v121, v160, v121, v160
	v_mul_f32_e32 v121, 0x3fcc422a, v121
	v_mul_f32_e32 v121, 0xbfb8aa3b, v121
	v_exp_f32_e32 v121, v121
	v_mul_f32_e32 v120, 0x3d372713, v124
	v_mul_f32_e32 v120, v124, v120
	v_mov_b32_e32 v123, v125
	v_add_f32_e32 v121, 1.0, v121
	v_rcp_f32_e32 v122, v121
	v_mul_f32_e32 v121, 0x3d372713, v125
	v_mul_f32_e32 v121, v125, v121
	v_fma_f32 v120, v124, v120, v124
	v_fmac_f32_e32 v123, v123, v121
	v_mul_f32_e32 v120, 0x3fcc422a, v120
	v_mul_f32_e32 v121, 0x3fcc422a, v123
	v_mul_f32_e32 v120, 0xbfb8aa3b, v120
	v_mul_f32_e32 v121, 0xbfb8aa3b, v121
	v_mul_f32_e32 v131, 0x3d372713, v158
	v_exp_f32_e32 v120, v120
	v_exp_f32_e32 v121, v121
	v_mul_f32_e32 v131, v158, v131
	v_fma_f32 v131, v158, v131, v158
	v_mul_f32_e32 v131, 0x3fcc422a, v131
	v_mul_f32_e32 v131, 0xbfb8aa3b, v131
	v_add_f32_e32 v120, 1.0, v120
	v_add_f32_e32 v121, 1.0, v121
	v_exp_f32_e32 v131, v131
	v_rcp_f32_e32 v120, v120
	v_rcp_f32_e32 v121, v121
	v_mul_f32_e32 v123, 0x3d372713, v161
	v_mul_f32_e32 v123, v161, v123
	v_mov_b32_e32 v130, v161
	v_fmac_f32_e32 v130, v130, v123
	v_add_f32_e32 v131, 1.0, v131
	v_mul_f32_e32 v123, 0x3fcc422a, v130
	v_mul_f32_e32 v130, 0x3d372713, v126
	v_rcp_f32_e32 v132, v131
	v_mul_f32_e32 v131, 0x3d372713, v127
	v_pk_mul_f32 v[124:125], v[124:125], v[120:121]
	v_mul_f32_e32 v120, 0x3d372713, v159
	v_mul_f32_e32 v130, v126, v130
	v_mul_f32_e32 v131, v127, v131
	v_mul_f32_e32 v120, v159, v120
	v_fma_f32 v130, v126, v130, v126
	v_fma_f32 v131, v127, v131, v127
	v_fma_f32 v120, v159, v120, v159
	v_mul_f32_e32 v130, 0x3fcc422a, v130
	v_mul_f32_e32 v131, 0x3fcc422a, v131
	v_mul_f32_e32 v120, 0x3fcc422a, v120
	v_mul_f32_e32 v123, 0xbfb8aa3b, v123
	v_mul_f32_e32 v130, 0xbfb8aa3b, v130
	v_mul_f32_e32 v131, 0xbfb8aa3b, v131
	v_mul_f32_e32 v120, 0xbfb8aa3b, v120
	v_exp_f32_e32 v123, v123
	v_exp_f32_e32 v130, v130
	v_exp_f32_e32 v131, v131
	v_exp_f32_e32 v120, v120
	v_add_f32_e32 v123, 1.0, v123
	v_add_f32_e32 v130, 1.0, v130
	v_add_f32_e32 v131, 1.0, v131
	v_add_f32_e32 v120, 1.0, v120
	v_rcp_f32_e32 v123, v123
	v_rcp_f32_e32 v130, v130
	v_rcp_f32_e32 v131, v131
	v_rcp_f32_e32 v133, v120
	v_pk_mul_f32 v[160:161], v[160:161], v[122:123]
	v_pk_mul_f32 v[126:127], v[126:127], v[130:131]
	v_pk_mul_f32 v[158:159], v[158:159], v[132:133]

.LBB0_344:
	s_add_u32 s30, s18, 0xb0080
	s_addc_u32 s31, s19, 0
	s_add_u32 s0, s14, 0x100
	v_mov_b32_e32 v0, 0
	s_addc_u32 s1, s15, 0
	s_mov_b32 s25, -2
	v_mov_b32_e32 v1, v0
	v_mov_b32_e32 v2, v0
	v_mov_b32_e32 v3, v0
	v_mov_b32_e32 v4, v0
	v_mov_b32_e32 v5, v0
	v_mov_b32_e32 v6, v0
	v_mov_b32_e32 v7, v0
	v_mov_b32_e32 v16, v0
	v_mov_b32_e32 v17, v0
	v_mov_b32_e32 v18, v0
	v_mov_b32_e32 v19, v0
	v_mov_b32_e32 v20, v0
	v_mov_b32_e32 v21, v0
	v_mov_b32_e32 v22, v0
	v_mov_b32_e32 v23, v0
	v_mov_b32_e32 v32, v0
	v_mov_b32_e32 v33, v0
	v_mov_b32_e32 v34, v0
	v_mov_b32_e32 v35, v0
	v_mov_b32_e32 v36, v0
	v_mov_b32_e32 v37, v0
	v_mov_b32_e32 v38, v0
	v_mov_b32_e32 v39, v0
	v_mov_b32_e32 v48, v0
	v_mov_b32_e32 v49, v0
	v_mov_b32_e32 v50, v0
	v_mov_b32_e32 v51, v0
	v_mov_b32_e32 v52, v0
	v_mov_b32_e32 v53, v0
	v_mov_b32_e32 v54, v0
	v_mov_b32_e32 v55, v0
	v_mov_b32_e32 v8, v0
	v_mov_b32_e32 v9, v0
	v_mov_b32_e32 v10, v0
	v_mov_b32_e32 v11, v0
	v_mov_b32_e32 v12, v0
	v_mov_b32_e32 v13, v0
	v_mov_b32_e32 v14, v0
	v_mov_b32_e32 v15, v0
	v_mov_b32_e32 v24, v0
	v_mov_b32_e32 v25, v0
	v_mov_b32_e32 v26, v0
	v_mov_b32_e32 v27, v0
	v_mov_b32_e32 v28, v0
	v_mov_b32_e32 v29, v0
	v_mov_b32_e32 v30, v0
	v_mov_b32_e32 v31, v0
	v_mov_b32_e32 v40, v0
	v_mov_b32_e32 v41, v0
	v_mov_b32_e32 v42, v0
	v_mov_b32_e32 v43, v0
	v_mov_b32_e32 v44, v0
	v_mov_b32_e32 v45, v0
	v_mov_b32_e32 v46, v0
	v_mov_b32_e32 v47, v0
	v_mov_b32_e32 v56, v0
	v_mov_b32_e32 v57, v0
	v_mov_b32_e32 v58, v0
	v_mov_b32_e32 v59, v0
	v_mov_b32_e32 v60, v0
	v_mov_b32_e32 v61, v0
	v_mov_b32_e32 v62, v0
	v_mov_b32_e32 v63, v0
	v_mov_b32_e32 v64, v0
	v_mov_b32_e32 v65, v0
	v_mov_b32_e32 v66, v0
	v_mov_b32_e32 v67, v0
	v_mov_b32_e32 v68, v0
	v_mov_b32_e32 v69, v0
	v_mov_b32_e32 v70, v0
	v_mov_b32_e32 v71, v0
	v_mov_b32_e32 v80, v0
	v_mov_b32_e32 v81, v0
	v_mov_b32_e32 v82, v0
	v_mov_b32_e32 v83, v0
	v_mov_b32_e32 v84, v0
	v_mov_b32_e32 v85, v0
	v_mov_b32_e32 v86, v0
	v_mov_b32_e32 v87, v0
	v_mov_b32_e32 v96, v0
	v_mov_b32_e32 v97, v0
	v_mov_b32_e32 v98, v0
	v_mov_b32_e32 v99, v0
	v_mov_b32_e32 v100, v0
	v_mov_b32_e32 v101, v0
	v_mov_b32_e32 v102, v0
	v_mov_b32_e32 v103, v0
	v_mov_b32_e32 v112, v0
	v_mov_b32_e32 v113, v0
	v_mov_b32_e32 v114, v0
	v_mov_b32_e32 v115, v0
	v_mov_b32_e32 v116, v0
	v_mov_b32_e32 v117, v0
	v_mov_b32_e32 v118, v0
	v_mov_b32_e32 v119, v0
	v_mov_b32_e32 v72, v0
	v_mov_b32_e32 v73, v0
	v_mov_b32_e32 v74, v0
	v_mov_b32_e32 v75, v0
	v_mov_b32_e32 v76, v0
	v_mov_b32_e32 v77, v0
	v_mov_b32_e32 v78, v0
	v_mov_b32_e32 v79, v0
	v_mov_b32_e32 v88, v0
	v_mov_b32_e32 v89, v0
	v_mov_b32_e32 v90, v0
	v_mov_b32_e32 v91, v0
	v_mov_b32_e32 v92, v0
	v_mov_b32_e32 v93, v0
	v_mov_b32_e32 v94, v0
	v_mov_b32_e32 v95, v0
	v_mov_b32_e32 v104, v0
	v_mov_b32_e32 v105, v0
	v_mov_b32_e32 v106, v0
	v_mov_b32_e32 v107, v0
	v_mov_b32_e32 v108, v0
	v_mov_b32_e32 v109, v0
	v_mov_b32_e32 v110, v0
	v_mov_b32_e32 v111, v0
	v_mov_b32_e32 v120, v0
	v_mov_b32_e32 v121, v0
	v_mov_b32_e32 v122, v0
	v_mov_b32_e32 v123, v0
	v_mov_b32_e32 v124, v0
	v_mov_b32_e32 v125, v0
	v_mov_b32_e32 v126, v0
	v_mov_b32_e32 v127, v0
	s_cmpk_gt_u32 s48, 0xff
	s_cbranch_scc0 .Lg2_enter
	s_barrier
	s_setprio 1
.Lg2_enter:
.LBB0_345:
	s_add_u32 s14, s30, 0xfff50080
	s_addc_u32 s15, s31, -1
	s_add_i32 s20, 16, 0x10000
	v_add_u32_e32 v130, s20, v160
	ds_read_b128 v[154:157], v130
	ds_read_b128 v[164:167], v130 offset:1024
	ds_read_b128 v[168:171], v130 offset:2048
	ds_read_b128 v[172:175], v130 offset:3072
	s_cmp_eq_u32 s25, 40
	s_cselect_b32 s19, s9, s15
	s_cselect_b32 s18, s8, s14
	s_cselect_b32 s15, s13, s1
	s_cselect_b32 s14, s12, s0
	v_lshl_add_u64 v[130:131], s[30:31], 0, v[150:151]
	s_add_i32 m0, s34, 0xc000
	ds_read_b128 v[176:179], v162
	ds_read_b128 v[180:183], v162 offset:1024
	ds_read_b128 v[184:187], v162 offset:2048
	ds_read_b128 v[188:191], v162 offset:3072
	ds_read_b128 v[192:195], v162 offset:4096
	ds_read_b128 v[196:199], v162 offset:5120
	ds_read_b128 v[200:203], v162 offset:6144
	ds_read_b128 v[204:207], v162 offset:7168
	global_load_lds_dwordx4 v[130:131], off
	v_lshl_add_u64 v[130:131], s[30:31], 0, v[152:153]
	s_add_i32 m0, s34, 0xe000
	s_nop 0
	global_load_lds_dwordx4 v[130:131], off
	s_add_i32 s42, 16, 0x14000
	v_add_u32_e32 v130, s42, v160
	ds_read_b128 v[208:211], v130
	ds_read_b128 v[212:215], v130 offset:1024
	ds_read_b128 v[216:219], v130 offset:2048
	ds_read_b128 v[220:223], v130 offset:3072
	s_waitcnt vmcnt(8) lgkmcnt(0)
	s_barrier
	v_mfma_f32_16x16x32_bf16 v[124:127], v[154:157], v[176:179], v[124:127]
	v_mfma_f32_16x16x32_bf16 v[120:123], v[168:171], v[176:179], v[120:123]
	v_mfma_f32_16x16x32_bf16 v[108:111], v[154:157], v[184:187], v[108:111]
	v_mfma_f32_16x16x32_bf16 v[104:107], v[168:171], v[184:187], v[104:107]
	v_mfma_f32_16x16x32_bf16 v[92:95], v[154:157], v[192:195], v[92:95]
	v_mfma_f32_16x16x32_bf16 v[88:91], v[168:171], v[192:195], v[88:91]
	v_mfma_f32_16x16x32_bf16 v[76:79], v[154:157], v[200:203], v[76:79]
	v_mfma_f32_16x16x32_bf16 v[72:75], v[168:171], v[200:203], v[72:75]
	v_mfma_f32_16x16x32_bf16 v[124:127], v[164:167], v[180:183], v[124:127]
	v_mfma_f32_16x16x32_bf16 v[120:123], v[172:175], v[180:183], v[120:123]
	v_mfma_f32_16x16x32_bf16 v[108:111], v[164:167], v[188:191], v[108:111]
	v_mfma_f32_16x16x32_bf16 v[104:107], v[172:175], v[188:191], v[104:107]
	v_mfma_f32_16x16x32_bf16 v[92:95], v[164:167], v[196:199], v[92:95]
	v_mfma_f32_16x16x32_bf16 v[88:91], v[172:175], v[196:199], v[88:91]
	v_mfma_f32_16x16x32_bf16 v[76:79], v[164:167], v[204:207], v[76:79]
	v_mfma_f32_16x16x32_bf16 v[72:75], v[172:175], v[204:207], v[72:75]
	v_mfma_f32_16x16x32_bf16 v[116:119], v[208:211], v[176:179], v[116:119]
	v_mfma_f32_16x16x32_bf16 v[112:115], v[216:219], v[176:179], v[112:115]
	v_mfma_f32_16x16x32_bf16 v[100:103], v[208:211], v[184:187], v[100:103]
	v_mfma_f32_16x16x32_bf16 v[96:99], v[216:219], v[184:187], v[96:99]
	v_mfma_f32_16x16x32_bf16 v[84:87], v[208:211], v[192:195], v[84:87]
	v_mfma_f32_16x16x32_bf16 v[80:83], v[216:219], v[192:195], v[80:83]
	v_mfma_f32_16x16x32_bf16 v[68:71], v[208:211], v[200:203], v[68:71]
	v_mfma_f32_16x16x32_bf16 v[64:67], v[216:219], v[200:203], v[64:67]
	v_mfma_f32_16x16x32_bf16 v[116:119], v[212:215], v[180:183], v[116:119]
	v_mfma_f32_16x16x32_bf16 v[112:115], v[220:223], v[180:183], v[112:115]
	v_mfma_f32_16x16x32_bf16 v[100:103], v[212:215], v[188:191], v[100:103]
	v_mfma_f32_16x16x32_bf16 v[96:99], v[220:223], v[188:191], v[96:99]
	v_mfma_f32_16x16x32_bf16 v[84:87], v[212:215], v[196:199], v[84:87]
	v_mfma_f32_16x16x32_bf16 v[80:83], v[220:223], v[196:199], v[80:83]
	v_mfma_f32_16x16x32_bf16 v[68:71], v[212:215], v[204:207], v[68:71]
	v_mfma_f32_16x16x32_bf16 v[64:67], v[220:223], v[204:207], v[64:67]
	s_barrier
	ds_read_b128 v[176:179], v162 offset:16384
	ds_read_b128 v[180:183], v162 offset:17408
	ds_read_b128 v[184:187], v162 offset:18432
	ds_read_b128 v[188:191], v162 offset:19456
	ds_read_b128 v[192:195], v162 offset:20480
	ds_read_b128 v[196:199], v162 offset:21504
	ds_read_b128 v[200:203], v162 offset:22528
	ds_read_b128 v[204:207], v162 offset:23552
	s_add_i32 s20, s20, s5
	v_lshl_add_u64 v[130:131], s[14:15], 0, v[128:129]
	s_mov_b32 m0, s20
	v_lshl_add_u64 v[132:133], s[14:15], 0, v[148:149]
	global_load_lds_dwordx4 v[130:131], off
	s_add_i32 m0, s20, 0x2000
	s_nop 0
	global_load_lds_dwordx4 v[132:133], off
	s_mov_b32 m0, s34
	v_lshl_add_u64 v[134:135], s[18:19], 0, v[144:145]
	global_load_lds_dwordx4 v[134:135], off
	v_lshl_add_u64 v[136:137], s[18:19], 0, v[146:147]
	s_mov_b32 m0, s35
	s_nop 0
	global_load_lds_dwordx4 v[136:137], off
	s_add_u32 s40, s14, 0xb0000
	s_addc_u32 s41, s15, 0
	s_add_i32 s20, s42, s5
	v_lshl_add_u64 v[138:139], s[40:41], 0, v[128:129]
	s_mov_b32 m0, s20
	s_nop 0
	global_load_lds_dwordx4 v[138:139], off
	v_lshl_add_u64 v[138:139], s[40:41], 0, v[148:149]
	s_add_i32 m0, s20, 0x2000
	s_nop 0
	global_load_lds_dwordx4 v[138:139], off
	s_waitcnt vmcnt(8) lgkmcnt(0)
	s_barrier
	v_mfma_f32_16x16x32_bf16 v[60:63], v[154:157], v[176:179], v[60:63]
	v_mfma_f32_16x16x32_bf16 v[56:59], v[168:171], v[176:179], v[56:59]
	v_mfma_f32_16x16x32_bf16 v[44:47], v[154:157], v[184:187], v[44:47]
	v_mfma_f32_16x16x32_bf16 v[40:43], v[168:171], v[184:187], v[40:43]
	v_mfma_f32_16x16x32_bf16 v[28:31], v[154:157], v[192:195], v[28:31]
	v_mfma_f32_16x16x32_bf16 v[24:27], v[168:171], v[192:195], v[24:27]
	v_mfma_f32_16x16x32_bf16 v[12:15], v[154:157], v[200:203], v[12:15]
	v_mfma_f32_16x16x32_bf16 v[8:11], v[168:171], v[200:203], v[8:11]
	v_mfma_f32_16x16x32_bf16 v[60:63], v[164:167], v[180:183], v[60:63]
	v_mfma_f32_16x16x32_bf16 v[56:59], v[172:175], v[180:183], v[56:59]
	v_mfma_f32_16x16x32_bf16 v[44:47], v[164:167], v[188:191], v[44:47]
	v_mfma_f32_16x16x32_bf16 v[40:43], v[172:175], v[188:191], v[40:43]
	v_mfma_f32_16x16x32_bf16 v[28:31], v[164:167], v[196:199], v[28:31]
	v_mfma_f32_16x16x32_bf16 v[24:27], v[172:175], v[196:199], v[24:27]
	v_mfma_f32_16x16x32_bf16 v[12:15], v[164:167], v[204:207], v[12:15]
	v_mfma_f32_16x16x32_bf16 v[8:11], v[172:175], v[204:207], v[8:11]
	v_mfma_f32_16x16x32_bf16 v[52:55], v[208:211], v[176:179], v[52:55]
	v_mfma_f32_16x16x32_bf16 v[48:51], v[216:219], v[176:179], v[48:51]
	v_mfma_f32_16x16x32_bf16 v[36:39], v[208:211], v[184:187], v[36:39]
	v_mfma_f32_16x16x32_bf16 v[32:35], v[216:219], v[184:187], v[32:35]
	v_mfma_f32_16x16x32_bf16 v[20:23], v[208:211], v[192:195], v[20:23]
	v_mfma_f32_16x16x32_bf16 v[16:19], v[216:219], v[192:195], v[16:19]
	v_mfma_f32_16x16x32_bf16 v[4:7], v[208:211], v[200:203], v[4:7]
	v_mfma_f32_16x16x32_bf16 v[0:3], v[216:219], v[200:203], v[0:3]
	v_mfma_f32_16x16x32_bf16 v[52:55], v[212:215], v[180:183], v[52:55]
	v_mfma_f32_16x16x32_bf16 v[48:51], v[220:223], v[180:183], v[48:51]
	v_mfma_f32_16x16x32_bf16 v[36:39], v[212:215], v[188:191], v[36:39]
	v_mfma_f32_16x16x32_bf16 v[32:35], v[220:223], v[188:191], v[32:35]
	v_mfma_f32_16x16x32_bf16 v[20:23], v[212:215], v[196:199], v[20:23]
	v_mfma_f32_16x16x32_bf16 v[16:19], v[220:223], v[196:199], v[16:19]
	v_mfma_f32_16x16x32_bf16 v[4:7], v[212:215], v[204:207], v[4:7]
	v_mfma_f32_16x16x32_bf16 v[0:3], v[220:223], v[204:207], v[0:3]
	s_add_i32 s20, 16, 0x18000
	v_add_u32_e32 v138, s20, v160
	s_barrier
	ds_read_b128 v[154:157], v138
	ds_read_b128 v[164:167], v138 offset:1024
	ds_read_b128 v[168:171], v138 offset:2048
	ds_read_b128 v[172:175], v138 offset:3072
	s_add_u32 s18, s18, 0xb0000
	s_addc_u32 s19, s19, 0
	s_mov_b32 m0, s36
	v_lshl_add_u64 v[158:159], s[18:19], 0, v[144:145]
	ds_read_b128 v[176:179], v162 offset:32768
	ds_read_b128 v[180:183], v162 offset:33792
	ds_read_b128 v[184:187], v162 offset:34816
	ds_read_b128 v[188:191], v162 offset:35840
	ds_read_b128 v[192:195], v162 offset:36864
	ds_read_b128 v[196:199], v162 offset:37888
	ds_read_b128 v[200:203], v162 offset:38912
	ds_read_b128 v[204:207], v162 offset:39936
	global_load_lds_dwordx4 v[158:159], off
	v_lshl_add_u64 v[158:159], s[18:19], 0, v[146:147]
	s_mov_b32 m0, s37
	s_nop 0
	global_load_lds_dwordx4 v[158:159], off
	s_add_i32 s18, 16, 0x1c000
	v_add_u32_e32 v138, s18, v160
	ds_read_b128 v[208:211], v138
	ds_read_b128 v[212:215], v138 offset:1024
	ds_read_b128 v[216:219], v138 offset:2048
	ds_read_b128 v[220:223], v138 offset:3072
	s_waitcnt vmcnt(8) lgkmcnt(0)
	s_barrier
	v_mfma_f32_16x16x32_bf16 v[124:127], v[154:157], v[176:179], v[124:127]
	v_mfma_f32_16x16x32_bf16 v[120:123], v[168:171], v[176:179], v[120:123]
	v_mfma_f32_16x16x32_bf16 v[108:111], v[154:157], v[184:187], v[108:111]
	v_mfma_f32_16x16x32_bf16 v[104:107], v[168:171], v[184:187], v[104:107]
	v_mfma_f32_16x16x32_bf16 v[92:95], v[154:157], v[192:195], v[92:95]
	v_mfma_f32_16x16x32_bf16 v[88:91], v[168:171], v[192:195], v[88:91]
	v_mfma_f32_16x16x32_bf16 v[76:79], v[154:157], v[200:203], v[76:79]
	v_mfma_f32_16x16x32_bf16 v[72:75], v[168:171], v[200:203], v[72:75]
	v_mfma_f32_16x16x32_bf16 v[124:127], v[164:167], v[180:183], v[124:127]
	v_mfma_f32_16x16x32_bf16 v[120:123], v[172:175], v[180:183], v[120:123]
	v_mfma_f32_16x16x32_bf16 v[108:111], v[164:167], v[188:191], v[108:111]
	v_mfma_f32_16x16x32_bf16 v[104:107], v[172:175], v[188:191], v[104:107]
	v_mfma_f32_16x16x32_bf16 v[92:95], v[164:167], v[196:199], v[92:95]
	v_mfma_f32_16x16x32_bf16 v[88:91], v[172:175], v[196:199], v[88:91]
	v_mfma_f32_16x16x32_bf16 v[76:79], v[164:167], v[204:207], v[76:79]
	v_mfma_f32_16x16x32_bf16 v[72:75], v[172:175], v[204:207], v[72:75]
	v_mfma_f32_16x16x32_bf16 v[116:119], v[208:211], v[176:179], v[116:119]
	v_mfma_f32_16x16x32_bf16 v[112:115], v[216:219], v[176:179], v[112:115]
	v_mfma_f32_16x16x32_bf16 v[100:103], v[208:211], v[184:187], v[100:103]
	v_mfma_f32_16x16x32_bf16 v[96:99], v[216:219], v[184:187], v[96:99]
	v_mfma_f32_16x16x32_bf16 v[84:87], v[208:211], v[192:195], v[84:87]
	v_mfma_f32_16x16x32_bf16 v[80:83], v[216:219], v[192:195], v[80:83]
	v_mfma_f32_16x16x32_bf16 v[68:71], v[208:211], v[200:203], v[68:71]
	v_mfma_f32_16x16x32_bf16 v[64:67], v[216:219], v[200:203], v[64:67]
	v_mfma_f32_16x16x32_bf16 v[116:119], v[212:215], v[180:183], v[116:119]
	v_mfma_f32_16x16x32_bf16 v[112:115], v[220:223], v[180:183], v[112:115]
	v_mfma_f32_16x16x32_bf16 v[100:103], v[212:215], v[188:191], v[100:103]
	v_mfma_f32_16x16x32_bf16 v[96:99], v[220:223], v[188:191], v[96:99]
	v_mfma_f32_16x16x32_bf16 v[84:87], v[212:215], v[196:199], v[84:87]
	v_mfma_f32_16x16x32_bf16 v[80:83], v[220:223], v[196:199], v[80:83]
	v_mfma_f32_16x16x32_bf16 v[68:71], v[212:215], v[204:207], v[68:71]
	v_mfma_f32_16x16x32_bf16 v[64:67], v[220:223], v[204:207], v[64:67]
	s_barrier
	ds_read_b128 v[176:179], v162 offset:49152
	ds_read_b128 v[180:183], v162 offset:50176
	ds_read_b128 v[184:187], v162 offset:51200
	ds_read_b128 v[188:191], v162 offset:52224
	ds_read_b128 v[192:195], v162 offset:53248
	ds_read_b128 v[196:199], v162 offset:54272
	ds_read_b128 v[200:203], v162 offset:55296
	ds_read_b128 v[204:207], v162 offset:56320
	s_add_i32 s19, s20, s5
	v_lshl_add_u64 v[130:131], v[130:131], 0, s[28:29]
	s_mov_b32 m0, s19
	s_nop 0
	global_load_lds_dwordx4 v[130:131], off
	v_lshl_add_u64 v[130:131], v[132:133], 0, s[28:29]
	s_add_i32 m0, s19, 0x2000
	s_nop 0
	global_load_lds_dwordx4 v[130:131], off
	s_mov_b32 m0, s44
	v_lshl_add_u64 v[130:131], v[134:135], 0, s[28:29]
	global_load_lds_dwordx4 v[130:131], off
	v_lshl_add_u64 v[130:131], v[136:137], 0, s[28:29]
	s_mov_b32 m0, s45
	s_nop 0
	global_load_lds_dwordx4 v[130:131], off
	s_add_u32 s14, s14, 0xb0080
	s_addc_u32 s15, s15, 0
	s_add_i32 s18, s18, s5
	v_lshl_add_u64 v[130:131], s[14:15], 0, v[128:129]
	s_mov_b32 m0, s18
	s_nop 0
	global_load_lds_dwordx4 v[130:131], off
	v_lshl_add_u64 v[130:131], s[14:15], 0, v[148:149]
	s_add_i32 m0, s18, 0x2000
	s_nop 0
	global_load_lds_dwordx4 v[130:131], off
	s_waitcnt vmcnt(8) lgkmcnt(0)
	s_barrier
	v_mfma_f32_16x16x32_bf16 v[60:63], v[154:157], v[176:179], v[60:63]
	v_mfma_f32_16x16x32_bf16 v[56:59], v[168:171], v[176:179], v[56:59]
	v_mfma_f32_16x16x32_bf16 v[44:47], v[154:157], v[184:187], v[44:47]
	v_mfma_f32_16x16x32_bf16 v[40:43], v[168:171], v[184:187], v[40:43]
	v_mfma_f32_16x16x32_bf16 v[28:31], v[154:157], v[192:195], v[28:31]
	v_mfma_f32_16x16x32_bf16 v[24:27], v[168:171], v[192:195], v[24:27]
	v_mfma_f32_16x16x32_bf16 v[12:15], v[154:157], v[200:203], v[12:15]
	v_mfma_f32_16x16x32_bf16 v[8:11], v[168:171], v[200:203], v[8:11]
	v_mfma_f32_16x16x32_bf16 v[60:63], v[164:167], v[180:183], v[60:63]
	v_mfma_f32_16x16x32_bf16 v[56:59], v[172:175], v[180:183], v[56:59]
	v_mfma_f32_16x16x32_bf16 v[44:47], v[164:167], v[188:191], v[44:47]
	v_mfma_f32_16x16x32_bf16 v[40:43], v[172:175], v[188:191], v[40:43]
	v_mfma_f32_16x16x32_bf16 v[28:31], v[164:167], v[196:199], v[28:31]
	v_mfma_f32_16x16x32_bf16 v[24:27], v[172:175], v[196:199], v[24:27]
	v_mfma_f32_16x16x32_bf16 v[12:15], v[164:167], v[204:207], v[12:15]
	v_mfma_f32_16x16x32_bf16 v[8:11], v[172:175], v[204:207], v[8:11]
	v_mfma_f32_16x16x32_bf16 v[52:55], v[208:211], v[176:179], v[52:55]
	v_mfma_f32_16x16x32_bf16 v[48:51], v[216:219], v[176:179], v[48:51]
	v_mfma_f32_16x16x32_bf16 v[36:39], v[208:211], v[184:187], v[36:39]
	v_mfma_f32_16x16x32_bf16 v[32:35], v[216:219], v[184:187], v[32:35]
	v_mfma_f32_16x16x32_bf16 v[20:23], v[208:211], v[192:195], v[20:23]
	v_mfma_f32_16x16x32_bf16 v[16:19], v[216:219], v[192:195], v[16:19]
	v_mfma_f32_16x16x32_bf16 v[4:7], v[208:211], v[200:203], v[4:7]
	v_mfma_f32_16x16x32_bf16 v[0:3], v[216:219], v[200:203], v[0:3]
	v_mfma_f32_16x16x32_bf16 v[52:55], v[212:215], v[180:183], v[52:55]
	v_mfma_f32_16x16x32_bf16 v[48:51], v[220:223], v[180:183], v[48:51]
	v_mfma_f32_16x16x32_bf16 v[36:39], v[212:215], v[188:191], v[36:39]
	v_mfma_f32_16x16x32_bf16 v[32:35], v[220:223], v[188:191], v[32:35]
	v_mfma_f32_16x16x32_bf16 v[20:23], v[212:215], v[196:199], v[20:23]
	v_mfma_f32_16x16x32_bf16 v[16:19], v[220:223], v[196:199], v[16:19]
	v_mfma_f32_16x16x32_bf16 v[4:7], v[212:215], v[204:207], v[4:7]
	v_mfma_f32_16x16x32_bf16 v[0:3], v[220:223], v[204:207], v[0:3]
	s_add_i32 s25, s25, 2
	s_add_u32 s30, s30, 0x100
	s_addc_u32 s31, s31, 0
	s_add_u32 s0, s0, 0x100
	s_addc_u32 s1, s1, 0
	s_cmp_gt_u32 s25, 41
	s_cbranch_scc1 .Lg2_exit
	s_barrier
	s_branch .LBB0_345

.Lg2_epi:
	s_setprio 0
	s_nop 0
	s_nop 0
	s_nop 0
	s_nop 0
	s_nop 0
	s_nop 0
	s_cmp_lt_i32 s47, 0
	s_cselect_b64 s[14:15], -1, 0
	s_cmp_gt_i32 s47, -1
	s_cbranch_scc1 .LBB0_348
	v_mul_f32_e32 v131, 0x3d372713, v120
	v_mul_f32_e32 v131, v120, v131
	v_fma_f32 v131, v120, v131, v120
	v_mul_f32_e32 v131, 0x3fcc422a, v131
	v_mul_f32_e32 v131, 0xbfb8aa3b, v131
	v_exp_f32_e32 v131, v131
	v_mul_f32_e32 v130, 0x3d372713, v124
	v_mul_f32_e32 v130, v124, v130
	v_fma_f32 v130, v124, v130, v124
	v_add_f32_e32 v131, 1.0, v131
	v_rcp_f32_e32 v132, v131
	v_mul_f32_e32 v131, 0x3d372713, v125
	v_mul_f32_e32 v131, v125, v131
	v_fma_f32 v131, v125, v131, v125
	v_mul_f32_e32 v130, 0x3fcc422a, v130
	v_mul_f32_e32 v131, 0x3fcc422a, v131
	v_mul_f32_e32 v130, 0xbfb8aa3b, v130
	v_mul_f32_e32 v131, 0xbfb8aa3b, v131
	v_mul_f32_e32 v135, 0x3d372713, v122
	v_exp_f32_e32 v130, v130
	v_exp_f32_e32 v131, v131
	v_mul_f32_e32 v135, v122, v135
	v_fma_f32 v135, v122, v135, v122
	v_mul_f32_e32 v135, 0x3fcc422a, v135
	v_mul_f32_e32 v135, 0xbfb8aa3b, v135
	v_add_f32_e32 v130, 1.0, v130
	v_add_f32_e32 v131, 1.0, v131
	v_exp_f32_e32 v135, v135
	v_rcp_f32_e32 v130, v130
	v_rcp_f32_e32 v131, v131
	v_mul_f32_e32 v133, 0x3d372713, v121
	v_add_f32_e32 v135, 1.0, v135
	v_mul_f32_e32 v134, 0x3d372713, v126
	v_rcp_f32_e32 v136, v135
	v_mul_f32_e32 v135, 0x3d372713, v127
	v_pk_mul_f32 v[124:125], v[124:125], v[130:131]
	v_mul_f32_e32 v130, 0x3d372713, v123
	v_mul_f32_e32 v133, v121, v133
	v_mul_f32_e32 v134, v126, v134
	v_mul_f32_e32 v135, v127, v135
	v_mul_f32_e32 v130, v123, v130
	v_fma_f32 v133, v121, v133, v121
	v_fma_f32 v134, v126, v134, v126
	v_fma_f32 v135, v127, v135, v127
	v_fma_f32 v130, v123, v130, v123
	v_mul_f32_e32 v133, 0x3fcc422a, v133
	v_mul_f32_e32 v134, 0x3fcc422a, v134
	v_mul_f32_e32 v135, 0x3fcc422a, v135
	v_mul_f32_e32 v130, 0x3fcc422a, v130
	v_mul_f32_e32 v133, 0xbfb8aa3b, v133
	v_mul_f32_e32 v134, 0xbfb8aa3b, v134
	v_mul_f32_e32 v135, 0xbfb8aa3b, v135
	v_mul_f32_e32 v130, 0xbfb8aa3b, v130
	v_exp_f32_e32 v133, v133
	v_exp_f32_e32 v134, v134
	v_exp_f32_e32 v135, v135
	v_exp_f32_e32 v130, v130
	v_add_f32_e32 v133, 1.0, v133
	v_add_f32_e32 v134, 1.0, v134
	v_add_f32_e32 v135, 1.0, v135
	v_add_f32_e32 v130, 1.0, v130
	v_rcp_f32_e32 v133, v133
	v_rcp_f32_e32 v134, v134
	v_rcp_f32_e32 v135, v135
	v_rcp_f32_e32 v137, v130
	v_pk_mul_f32 v[120:121], v[120:121], v[132:133]
	v_pk_mul_f32 v[126:127], v[126:127], v[134:135]
	v_pk_mul_f32 v[122:123], v[122:123], v[136:137]

.LBB0_390:
	v_mov_b64_e32 v[0:1], 0x1080
	s_ashr_i32 s13, s12, 31
	v_cmp_lt_i64_e32 vcc, s[30:31], v[0:1]
	s_lshl_b64 s[24:25], s[12:13], 19
	v_readlane_b32 s30, v252, 55
	v_readlane_b32 s31, v252, 56
	s_add_u32 s40, s30, s24
	s_addc_u32 s41, s31, s25
	v_lshl_add_u32 v154, s20, 8, v143
	v_readlane_b32 s30, v252, 43
	v_ashrrev_i32_e32 v155, 31, v154
	v_readlane_b32 s31, v252, 44
	s_and_b64 s[24:25], vcc, exec
	s_cselect_b32 s1, s41, s19
	v_lshl_add_u64 v[0:1], v[154:155], 2, s[30:31]
	global_load_dword v165, v[0:1], off
	global_load_dword v164, v[0:1], off offset:64
	global_load_dword v163, v[0:1], off offset:128
	global_load_dword v162, v[0:1], off offset:192
	global_load_dword v161, v[0:1], off offset:512
	global_load_dword v160, v[0:1], off offset:576
	global_load_dword v159, v[0:1], off offset:640
	global_load_dword v155, v[0:1], off offset:704
	s_cselect_b32 s13, s40, s18
	s_ashr_i32 s9, s8, 31
	s_lshl_b64 s[24:25], s[8:9], 19
	s_add_u32 s42, s16, s24
	s_addc_u32 s43, s17, s25
	s_and_b64 s[24:25], vcc, exec
	s_cselect_b32 s9, s43, s15
	s_cselect_b32 s24, s42, s14
	s_add_u32 s30, s18, 0x40080
	s_addc_u32 s31, s19, 0
	s_add_u32 s25, s14, 0x100
	v_mov_b32_e32 v8, 0
	s_addc_u32 s47, s15, 0
	s_mov_b32 s92, -2
	v_mov_b32_e32 v9, v8
	v_mov_b32_e32 v10, v8
	v_mov_b32_e32 v11, v8
	v_mov_b32_e32 v12, v8
	v_mov_b32_e32 v13, v8
	v_mov_b32_e32 v14, v8
	v_mov_b32_e32 v15, v8
	v_mov_b32_e32 v24, v8
	v_mov_b32_e32 v25, v8
	v_mov_b32_e32 v26, v8
	v_mov_b32_e32 v27, v8
	v_mov_b32_e32 v28, v8
	v_mov_b32_e32 v29, v8
	v_mov_b32_e32 v30, v8
	v_mov_b32_e32 v31, v8
	v_mov_b32_e32 v40, v8
	v_mov_b32_e32 v41, v8
	v_mov_b32_e32 v42, v8
	v_mov_b32_e32 v43, v8
	v_mov_b32_e32 v44, v8
	v_mov_b32_e32 v45, v8
	v_mov_b32_e32 v46, v8
	v_mov_b32_e32 v47, v8
	v_mov_b32_e32 v56, v8
	v_mov_b32_e32 v57, v8
	v_mov_b32_e32 v58, v8
	v_mov_b32_e32 v59, v8
	v_mov_b32_e32 v60, v8
	v_mov_b32_e32 v61, v8
	v_mov_b32_e32 v62, v8
	v_mov_b32_e32 v63, v8
	v_mov_b32_e32 v0, v8
	v_mov_b32_e32 v1, v8
	v_mov_b32_e32 v2, v8
	v_mov_b32_e32 v3, v8
	v_mov_b32_e32 v4, v8
	v_mov_b32_e32 v5, v8
	v_mov_b32_e32 v6, v8
	v_mov_b32_e32 v7, v8
	v_mov_b32_e32 v16, v8
	v_mov_b32_e32 v17, v8
	v_mov_b32_e32 v18, v8
	v_mov_b32_e32 v19, v8
	v_mov_b32_e32 v20, v8
	v_mov_b32_e32 v21, v8
	v_mov_b32_e32 v22, v8
	v_mov_b32_e32 v23, v8
	v_mov_b32_e32 v32, v8
	v_mov_b32_e32 v33, v8
	v_mov_b32_e32 v34, v8
	v_mov_b32_e32 v35, v8
	v_mov_b32_e32 v36, v8
	v_mov_b32_e32 v37, v8
	v_mov_b32_e32 v38, v8
	v_mov_b32_e32 v39, v8
	v_mov_b32_e32 v48, v8
	v_mov_b32_e32 v49, v8
	v_mov_b32_e32 v50, v8
	v_mov_b32_e32 v51, v8
	v_mov_b32_e32 v52, v8
	v_mov_b32_e32 v53, v8
	v_mov_b32_e32 v54, v8
	v_mov_b32_e32 v55, v8
	v_mov_b32_e32 v72, v8
	v_mov_b32_e32 v73, v8
	v_mov_b32_e32 v74, v8
	v_mov_b32_e32 v75, v8
	v_mov_b32_e32 v76, v8
	v_mov_b32_e32 v77, v8
	v_mov_b32_e32 v78, v8
	v_mov_b32_e32 v79, v8
	v_mov_b32_e32 v88, v8
	v_mov_b32_e32 v89, v8
	v_mov_b32_e32 v90, v8
	v_mov_b32_e32 v91, v8
	v_mov_b32_e32 v92, v8
	v_mov_b32_e32 v93, v8
	v_mov_b32_e32 v94, v8
	v_mov_b32_e32 v95, v8
	v_mov_b32_e32 v104, v8
	v_mov_b32_e32 v105, v8
	v_mov_b32_e32 v106, v8
	v_mov_b32_e32 v107, v8
	v_mov_b32_e32 v108, v8
	v_mov_b32_e32 v109, v8
	v_mov_b32_e32 v110, v8
	v_mov_b32_e32 v111, v8
	v_mov_b32_e32 v120, v8
	v_mov_b32_e32 v121, v8
	v_mov_b32_e32 v122, v8
	v_mov_b32_e32 v123, v8
	v_mov_b32_e32 v124, v8
	v_mov_b32_e32 v125, v8
	v_mov_b32_e32 v126, v8
	v_mov_b32_e32 v127, v8
	v_mov_b32_e32 v64, v8
	v_mov_b32_e32 v65, v8
	v_mov_b32_e32 v66, v8
	v_mov_b32_e32 v67, v8
	v_mov_b32_e32 v68, v8
	v_mov_b32_e32 v69, v8
	v_mov_b32_e32 v70, v8
	v_mov_b32_e32 v71, v8
	v_mov_b32_e32 v80, v8
	v_mov_b32_e32 v81, v8
	v_mov_b32_e32 v82, v8
	v_mov_b32_e32 v83, v8
	v_mov_b32_e32 v84, v8
	v_mov_b32_e32 v85, v8
	v_mov_b32_e32 v86, v8
	v_mov_b32_e32 v87, v8
	v_mov_b32_e32 v96, v8
	v_mov_b32_e32 v97, v8
	v_mov_b32_e32 v98, v8
	v_mov_b32_e32 v99, v8
	v_mov_b32_e32 v100, v8
	v_mov_b32_e32 v101, v8
	v_mov_b32_e32 v102, v8
	v_mov_b32_e32 v103, v8
	v_mov_b32_e32 v112, v8
	v_mov_b32_e32 v113, v8
	v_mov_b32_e32 v114, v8
	v_mov_b32_e32 v115, v8
	v_mov_b32_e32 v116, v8
	v_mov_b32_e32 v117, v8
	v_mov_b32_e32 v118, v8
	v_mov_b32_e32 v119, v8
	s_cmpk_gt_u32 s4, 0xff
	s_cbranch_scc0 .Lg1_enter
	s_barrier
	s_setprio 1
.Lg1_enter:
.LBB0_391:
	s_add_u32 s14, s30, 0xfffc0080
	s_addc_u32 s15, s31, -1
	s_add_i32 s20, 16, 0x10000
	v_add_u32_e32 v130, s20, v156
	ds_read_b128 v[166:169], v130
	ds_read_b128 v[170:173], v130 offset:1024
	ds_read_b128 v[174:177], v130 offset:2048
	ds_read_b128 v[178:181], v130 offset:3072
	s_cmp_eq_u32 s92, 12
	s_cselect_b32 s19, s1, s15
	s_cselect_b32 s18, s13, s14
	s_cselect_b32 s15, s9, s47
	s_cselect_b32 s14, s24, s25
	v_lshl_add_u64 v[130:131], s[30:31], 0, v[150:151]
	s_add_i32 m0, s34, 0xc000
	ds_read_b128 v[182:185], v158
	ds_read_b128 v[186:189], v158 offset:1024
	ds_read_b128 v[190:193], v158 offset:2048
	ds_read_b128 v[194:197], v158 offset:3072
	ds_read_b128 v[198:201], v158 offset:4096
	ds_read_b128 v[202:205], v158 offset:5120
	ds_read_b128 v[206:209], v158 offset:6144
	ds_read_b128 v[210:213], v158 offset:7168
	global_load_lds_dwordx4 v[130:131], off
	v_lshl_add_u64 v[130:131], s[30:31], 0, v[152:153]
	s_add_i32 m0, s34, 0xe000
	s_nop 0
	global_load_lds_dwordx4 v[130:131], off
	s_add_i32 s50, 16, 0x14000
	v_add_u32_e32 v130, s50, v156
	ds_read_b128 v[214:217], v130
	ds_read_b128 v[218:221], v130 offset:1024
	ds_read_b128 v[222:225], v130 offset:2048
	ds_read_b128 v[226:229], v130 offset:3072
	s_waitcnt vmcnt(8) lgkmcnt(0)
	s_barrier
	v_mfma_f32_16x16x32_bf16 v[116:119], v[166:169], v[182:185], v[116:119]
	v_mfma_f32_16x16x32_bf16 v[112:115], v[174:177], v[182:185], v[112:115]
	v_mfma_f32_16x16x32_bf16 v[100:103], v[166:169], v[190:193], v[100:103]
	v_mfma_f32_16x16x32_bf16 v[96:99], v[174:177], v[190:193], v[96:99]
	v_mfma_f32_16x16x32_bf16 v[84:87], v[166:169], v[198:201], v[84:87]
	v_mfma_f32_16x16x32_bf16 v[80:83], v[174:177], v[198:201], v[80:83]
	v_mfma_f32_16x16x32_bf16 v[68:71], v[166:169], v[206:209], v[68:71]
	v_mfma_f32_16x16x32_bf16 v[64:67], v[174:177], v[206:209], v[64:67]
	v_mfma_f32_16x16x32_bf16 v[116:119], v[170:173], v[186:189], v[116:119]
	v_mfma_f32_16x16x32_bf16 v[112:115], v[178:181], v[186:189], v[112:115]
	v_mfma_f32_16x16x32_bf16 v[100:103], v[170:173], v[194:197], v[100:103]
	v_mfma_f32_16x16x32_bf16 v[96:99], v[178:181], v[194:197], v[96:99]
	v_mfma_f32_16x16x32_bf16 v[84:87], v[170:173], v[202:205], v[84:87]
	v_mfma_f32_16x16x32_bf16 v[80:83], v[178:181], v[202:205], v[80:83]
	v_mfma_f32_16x16x32_bf16 v[68:71], v[170:173], v[210:213], v[68:71]
	v_mfma_f32_16x16x32_bf16 v[64:67], v[178:181], v[210:213], v[64:67]
	v_mfma_f32_16x16x32_bf16 v[124:127], v[214:217], v[182:185], v[124:127]
	v_mfma_f32_16x16x32_bf16 v[120:123], v[222:225], v[182:185], v[120:123]
	v_mfma_f32_16x16x32_bf16 v[108:111], v[214:217], v[190:193], v[108:111]
	v_mfma_f32_16x16x32_bf16 v[104:107], v[222:225], v[190:193], v[104:107]
	v_mfma_f32_16x16x32_bf16 v[92:95], v[214:217], v[198:201], v[92:95]
	v_mfma_f32_16x16x32_bf16 v[88:91], v[222:225], v[198:201], v[88:91]
	v_mfma_f32_16x16x32_bf16 v[76:79], v[214:217], v[206:209], v[76:79]
	v_mfma_f32_16x16x32_bf16 v[72:75], v[222:225], v[206:209], v[72:75]
	v_mfma_f32_16x16x32_bf16 v[124:127], v[218:221], v[186:189], v[124:127]
	v_mfma_f32_16x16x32_bf16 v[120:123], v[226:229], v[186:189], v[120:123]
	v_mfma_f32_16x16x32_bf16 v[108:111], v[218:221], v[194:197], v[108:111]
	v_mfma_f32_16x16x32_bf16 v[104:107], v[226:229], v[194:197], v[104:107]
	v_mfma_f32_16x16x32_bf16 v[92:95], v[218:221], v[202:205], v[92:95]
	v_mfma_f32_16x16x32_bf16 v[88:91], v[226:229], v[202:205], v[88:91]
	v_mfma_f32_16x16x32_bf16 v[76:79], v[218:221], v[210:213], v[76:79]
	v_mfma_f32_16x16x32_bf16 v[72:75], v[226:229], v[210:213], v[72:75]
	s_barrier
	ds_read_b128 v[182:185], v158 offset:16384
	ds_read_b128 v[186:189], v158 offset:17408
	ds_read_b128 v[190:193], v158 offset:18432
	ds_read_b128 v[194:197], v158 offset:19456
	ds_read_b128 v[198:201], v158 offset:20480
	ds_read_b128 v[202:205], v158 offset:21504
	ds_read_b128 v[206:209], v158 offset:22528
	ds_read_b128 v[210:213], v158 offset:23552
	s_add_i32 s20, s20, s5
	v_lshl_add_u64 v[130:131], s[14:15], 0, v[128:129]
	s_mov_b32 m0, s20
	v_lshl_add_u64 v[132:133], s[14:15], 0, v[144:145]
	global_load_lds_dwordx4 v[130:131], off
	s_add_i32 m0, s20, 0x2000
	s_nop 0
	global_load_lds_dwordx4 v[132:133], off
	s_mov_b32 m0, s34
	v_lshl_add_u64 v[134:135], s[18:19], 0, v[148:149]
	global_load_lds_dwordx4 v[134:135], off
	v_lshl_add_u64 v[136:137], s[18:19], 0, v[146:147]
	s_mov_b32 m0, s35
	s_nop 0
	global_load_lds_dwordx4 v[136:137], off
	s_add_u32 s48, s14, 0x40000
	s_addc_u32 s49, s15, 0
	s_add_i32 s20, s50, s5
	v_lshl_add_u64 v[138:139], s[48:49], 0, v[128:129]
	s_mov_b32 m0, s20
	s_nop 0
	global_load_lds_dwordx4 v[138:139], off
	v_lshl_add_u64 v[138:139], s[48:49], 0, v[144:145]
	s_add_i32 m0, s20, 0x2000
	s_nop 0
	global_load_lds_dwordx4 v[138:139], off
	s_waitcnt vmcnt(8) lgkmcnt(0)
	s_barrier
	v_mfma_f32_16x16x32_bf16 v[52:55], v[166:169], v[182:185], v[52:55]
	v_mfma_f32_16x16x32_bf16 v[48:51], v[174:177], v[182:185], v[48:51]
	v_mfma_f32_16x16x32_bf16 v[36:39], v[166:169], v[190:193], v[36:39]
	v_mfma_f32_16x16x32_bf16 v[32:35], v[174:177], v[190:193], v[32:35]
	v_mfma_f32_16x16x32_bf16 v[20:23], v[166:169], v[198:201], v[20:23]
	v_mfma_f32_16x16x32_bf16 v[16:19], v[174:177], v[198:201], v[16:19]
	v_mfma_f32_16x16x32_bf16 v[4:7], v[166:169], v[206:209], v[4:7]
	v_mfma_f32_16x16x32_bf16 v[0:3], v[174:177], v[206:209], v[0:3]
	v_mfma_f32_16x16x32_bf16 v[52:55], v[170:173], v[186:189], v[52:55]
	v_mfma_f32_16x16x32_bf16 v[48:51], v[178:181], v[186:189], v[48:51]
	v_mfma_f32_16x16x32_bf16 v[36:39], v[170:173], v[194:197], v[36:39]
	v_mfma_f32_16x16x32_bf16 v[32:35], v[178:181], v[194:197], v[32:35]
	v_mfma_f32_16x16x32_bf16 v[20:23], v[170:173], v[202:205], v[20:23]
	v_mfma_f32_16x16x32_bf16 v[16:19], v[178:181], v[202:205], v[16:19]
	v_mfma_f32_16x16x32_bf16 v[4:7], v[170:173], v[210:213], v[4:7]
	v_mfma_f32_16x16x32_bf16 v[0:3], v[178:181], v[210:213], v[0:3]
	v_mfma_f32_16x16x32_bf16 v[60:63], v[214:217], v[182:185], v[60:63]
	v_mfma_f32_16x16x32_bf16 v[56:59], v[222:225], v[182:185], v[56:59]
	v_mfma_f32_16x16x32_bf16 v[44:47], v[214:217], v[190:193], v[44:47]
	v_mfma_f32_16x16x32_bf16 v[40:43], v[222:225], v[190:193], v[40:43]
	v_mfma_f32_16x16x32_bf16 v[28:31], v[214:217], v[198:201], v[28:31]
	v_mfma_f32_16x16x32_bf16 v[24:27], v[222:225], v[198:201], v[24:27]
	v_mfma_f32_16x16x32_bf16 v[12:15], v[214:217], v[206:209], v[12:15]
	v_mfma_f32_16x16x32_bf16 v[8:11], v[222:225], v[206:209], v[8:11]
	v_mfma_f32_16x16x32_bf16 v[60:63], v[218:221], v[186:189], v[60:63]
	v_mfma_f32_16x16x32_bf16 v[56:59], v[226:229], v[186:189], v[56:59]
	v_mfma_f32_16x16x32_bf16 v[44:47], v[218:221], v[194:197], v[44:47]
	v_mfma_f32_16x16x32_bf16 v[40:43], v[226:229], v[194:197], v[40:43]
	v_mfma_f32_16x16x32_bf16 v[28:31], v[218:221], v[202:205], v[28:31]
	v_mfma_f32_16x16x32_bf16 v[24:27], v[226:229], v[202:205], v[24:27]
	v_mfma_f32_16x16x32_bf16 v[12:15], v[218:221], v[210:213], v[12:15]
	v_mfma_f32_16x16x32_bf16 v[8:11], v[226:229], v[210:213], v[8:11]
	s_add_i32 s20, 16, 0x18000
	v_add_u32_e32 v138, s20, v156
	s_barrier
	ds_read_b128 v[166:169], v138
	ds_read_b128 v[170:173], v138 offset:1024
	ds_read_b128 v[174:177], v138 offset:2048
	ds_read_b128 v[178:181], v138 offset:3072
	s_add_u32 s18, s18, 0x40000
	s_addc_u32 s19, s19, 0
	s_mov_b32 m0, s36
	v_lshl_add_u64 v[214:215], s[18:19], 0, v[148:149]
	ds_read_b128 v[182:185], v158 offset:32768
	ds_read_b128 v[186:189], v158 offset:33792
	ds_read_b128 v[190:193], v158 offset:34816
	ds_read_b128 v[194:197], v158 offset:35840
	ds_read_b128 v[198:201], v158 offset:36864
	ds_read_b128 v[202:205], v158 offset:37888
	ds_read_b128 v[206:209], v158 offset:38912
	ds_read_b128 v[210:213], v158 offset:39936
	global_load_lds_dwordx4 v[214:215], off
	v_lshl_add_u64 v[214:215], s[18:19], 0, v[146:147]
	s_mov_b32 m0, s37
	s_nop 0
	global_load_lds_dwordx4 v[214:215], off
	s_add_i32 s18, 16, 0x1c000
	v_add_u32_e32 v138, s18, v156
	ds_read_b128 v[214:217], v138
	ds_read_b128 v[218:221], v138 offset:1024
	ds_read_b128 v[222:225], v138 offset:2048
	ds_read_b128 v[226:229], v138 offset:3072
	s_waitcnt vmcnt(8) lgkmcnt(0)
	s_barrier
	v_mfma_f32_16x16x32_bf16 v[116:119], v[166:169], v[182:185], v[116:119]
	v_mfma_f32_16x16x32_bf16 v[112:115], v[174:177], v[182:185], v[112:115]
	v_mfma_f32_16x16x32_bf16 v[100:103], v[166:169], v[190:193], v[100:103]
	v_mfma_f32_16x16x32_bf16 v[96:99], v[174:177], v[190:193], v[96:99]
	v_mfma_f32_16x16x32_bf16 v[84:87], v[166:169], v[198:201], v[84:87]
	v_mfma_f32_16x16x32_bf16 v[80:83], v[174:177], v[198:201], v[80:83]
	v_mfma_f32_16x16x32_bf16 v[68:71], v[166:169], v[206:209], v[68:71]
	v_mfma_f32_16x16x32_bf16 v[64:67], v[174:177], v[206:209], v[64:67]
	v_mfma_f32_16x16x32_bf16 v[116:119], v[170:173], v[186:189], v[116:119]
	v_mfma_f32_16x16x32_bf16 v[112:115], v[178:181], v[186:189], v[112:115]
	v_mfma_f32_16x16x32_bf16 v[100:103], v[170:173], v[194:197], v[100:103]
	v_mfma_f32_16x16x32_bf16 v[96:99], v[178:181], v[194:197], v[96:99]
	v_mfma_f32_16x16x32_bf16 v[84:87], v[170:173], v[202:205], v[84:87]
	v_mfma_f32_16x16x32_bf16 v[80:83], v[178:181], v[202:205], v[80:83]
	v_mfma_f32_16x16x32_bf16 v[68:71], v[170:173], v[210:213], v[68:71]
	v_mfma_f32_16x16x32_bf16 v[64:67], v[178:181], v[210:213], v[64:67]
	v_mfma_f32_16x16x32_bf16 v[124:127], v[214:217], v[182:185], v[124:127]
	v_mfma_f32_16x16x32_bf16 v[120:123], v[222:225], v[182:185], v[120:123]
	v_mfma_f32_16x16x32_bf16 v[108:111], v[214:217], v[190:193], v[108:111]
	v_mfma_f32_16x16x32_bf16 v[104:107], v[222:225], v[190:193], v[104:107]
	v_mfma_f32_16x16x32_bf16 v[92:95], v[214:217], v[198:201], v[92:95]
	v_mfma_f32_16x16x32_bf16 v[88:91], v[222:225], v[198:201], v[88:91]
	v_mfma_f32_16x16x32_bf16 v[76:79], v[214:217], v[206:209], v[76:79]
	v_mfma_f32_16x16x32_bf16 v[72:75], v[222:225], v[206:209], v[72:75]
	v_mfma_f32_16x16x32_bf16 v[124:127], v[218:221], v[186:189], v[124:127]
	v_mfma_f32_16x16x32_bf16 v[120:123], v[226:229], v[186:189], v[120:123]
	v_mfma_f32_16x16x32_bf16 v[108:111], v[218:221], v[194:197], v[108:111]
	v_mfma_f32_16x16x32_bf16 v[104:107], v[226:229], v[194:197], v[104:107]
	v_mfma_f32_16x16x32_bf16 v[92:95], v[218:221], v[202:205], v[92:95]
	v_mfma_f32_16x16x32_bf16 v[88:91], v[226:229], v[202:205], v[88:91]
	v_mfma_f32_16x16x32_bf16 v[76:79], v[218:221], v[210:213], v[76:79]
	v_mfma_f32_16x16x32_bf16 v[72:75], v[226:229], v[210:213], v[72:75]
	s_barrier
	ds_read_b128 v[182:185], v158 offset:49152
	ds_read_b128 v[186:189], v158 offset:50176
	ds_read_b128 v[190:193], v158 offset:51200
	ds_read_b128 v[194:197], v158 offset:52224
	ds_read_b128 v[198:201], v158 offset:53248
	ds_read_b128 v[202:205], v158 offset:54272
	ds_read_b128 v[206:209], v158 offset:55296
	ds_read_b128 v[210:213], v158 offset:56320
	s_add_i32 s19, s20, s5
	v_lshl_add_u64 v[130:131], v[130:131], 0, s[28:29]
	s_mov_b32 m0, s19
	s_nop 0
	global_load_lds_dwordx4 v[130:131], off
	v_lshl_add_u64 v[130:131], v[132:133], 0, s[28:29]
	s_add_i32 m0, s19, 0x2000
	s_nop 0
	global_load_lds_dwordx4 v[130:131], off
	s_mov_b32 m0, s44
	v_lshl_add_u64 v[130:131], v[134:135], 0, s[28:29]
	global_load_lds_dwordx4 v[130:131], off
	v_lshl_add_u64 v[130:131], v[136:137], 0, s[28:29]
	s_mov_b32 m0, s45
	s_nop 0
	global_load_lds_dwordx4 v[130:131], off
	s_add_u32 s14, s14, 0x40080
	s_addc_u32 s15, s15, 0
	s_add_i32 s18, s18, s5
	v_lshl_add_u64 v[130:131], s[14:15], 0, v[128:129]
	s_mov_b32 m0, s18
	s_nop 0
	global_load_lds_dwordx4 v[130:131], off
	v_lshl_add_u64 v[130:131], s[14:15], 0, v[144:145]
	s_add_i32 m0, s18, 0x2000
	s_nop 0
	global_load_lds_dwordx4 v[130:131], off
	s_waitcnt vmcnt(8) lgkmcnt(0)
	s_barrier
	v_mfma_f32_16x16x32_bf16 v[52:55], v[166:169], v[182:185], v[52:55]
	v_mfma_f32_16x16x32_bf16 v[48:51], v[174:177], v[182:185], v[48:51]
	v_mfma_f32_16x16x32_bf16 v[36:39], v[166:169], v[190:193], v[36:39]
	v_mfma_f32_16x16x32_bf16 v[32:35], v[174:177], v[190:193], v[32:35]
	v_mfma_f32_16x16x32_bf16 v[20:23], v[166:169], v[198:201], v[20:23]
	v_mfma_f32_16x16x32_bf16 v[16:19], v[174:177], v[198:201], v[16:19]
	v_mfma_f32_16x16x32_bf16 v[4:7], v[166:169], v[206:209], v[4:7]
	v_mfma_f32_16x16x32_bf16 v[0:3], v[174:177], v[206:209], v[0:3]
	v_mfma_f32_16x16x32_bf16 v[52:55], v[170:173], v[186:189], v[52:55]
	v_mfma_f32_16x16x32_bf16 v[48:51], v[178:181], v[186:189], v[48:51]
	v_mfma_f32_16x16x32_bf16 v[36:39], v[170:173], v[194:197], v[36:39]
	v_mfma_f32_16x16x32_bf16 v[32:35], v[178:181], v[194:197], v[32:35]
	v_mfma_f32_16x16x32_bf16 v[20:23], v[170:173], v[202:205], v[20:23]
	v_mfma_f32_16x16x32_bf16 v[16:19], v[178:181], v[202:205], v[16:19]
	v_mfma_f32_16x16x32_bf16 v[4:7], v[170:173], v[210:213], v[4:7]
	v_mfma_f32_16x16x32_bf16 v[0:3], v[178:181], v[210:213], v[0:3]
	v_mfma_f32_16x16x32_bf16 v[60:63], v[214:217], v[182:185], v[60:63]
	v_mfma_f32_16x16x32_bf16 v[56:59], v[222:225], v[182:185], v[56:59]
	v_mfma_f32_16x16x32_bf16 v[44:47], v[214:217], v[190:193], v[44:47]
	v_mfma_f32_16x16x32_bf16 v[40:43], v[222:225], v[190:193], v[40:43]
	v_mfma_f32_16x16x32_bf16 v[28:31], v[214:217], v[198:201], v[28:31]
	v_mfma_f32_16x16x32_bf16 v[24:27], v[222:225], v[198:201], v[24:27]
	v_mfma_f32_16x16x32_bf16 v[12:15], v[214:217], v[206:209], v[12:15]
	v_mfma_f32_16x16x32_bf16 v[8:11], v[222:225], v[206:209], v[8:11]
	v_mfma_f32_16x16x32_bf16 v[60:63], v[218:221], v[186:189], v[60:63]
	v_mfma_f32_16x16x32_bf16 v[56:59], v[226:229], v[186:189], v[56:59]
	v_mfma_f32_16x16x32_bf16 v[44:47], v[218:221], v[194:197], v[44:47]
	v_mfma_f32_16x16x32_bf16 v[40:43], v[226:229], v[194:197], v[40:43]
	v_mfma_f32_16x16x32_bf16 v[28:31], v[218:221], v[202:205], v[28:31]
	v_mfma_f32_16x16x32_bf16 v[24:27], v[226:229], v[202:205], v[24:27]
	v_mfma_f32_16x16x32_bf16 v[12:15], v[218:221], v[210:213], v[12:15]
	v_mfma_f32_16x16x32_bf16 v[8:11], v[226:229], v[210:213], v[8:11]
	s_add_i32 s92, s92, 2
	s_add_u32 s30, s30, 0x100
	s_addc_u32 s31, s31, 0
	s_add_u32 s25, s25, 0x100
	s_addc_u32 s47, s47, 0
	s_cmp_gt_u32 s92, 13
	s_cbranch_scc1 .Lg1_exit
	s_barrier
	s_branch .LBB0_391

.Lg1_epi:
	s_setprio 0
	s_nop 0
	s_nop 0
	s_nop 0
	s_nop 0
	s_nop 0
	s_nop 0
	s_waitcnt vmcnt(0)
	v_fmamk_f32 v132, v165, 0x3a800000, v235
	v_cmp_gt_f32_e32 vcc, s86, v132
	v_mul_f32_e32 v133, 0x4b800000, v132
	v_pk_mul_f32 v[126:127], v[118:119], v[126:127]
	v_cndmask_b32_e32 v132, v132, v133, vcc
	v_rsq_f32_e32 v132, v132
	v_pk_mul_f32 v[122:123], v[114:115], v[122:123]
	v_lshl_or_b32 v130, s0, 7, v157
	v_ashrrev_i32_e32 v131, 31, v130
	v_mul_f32_e32 v133, 0x45800000, v132
	v_cndmask_b32_e32 v132, v132, v133, vcc
	v_mul_f32_e32 v133, 0xbfb8aa3b, v132
	v_mul_f32_e32 v135, v133, v112
	v_exp_f32_e32 v135, v135
	v_mul_f32_e32 v134, v133, v116
	v_exp_f32_e32 v134, v134
	v_mul_f32_e32 v132, v132, v132
	v_add_f32_e32 v135, 1.0, v135
	v_rcp_f32_e32 v136, v135
	v_mul_f32_e32 v135, v133, v117
	v_exp_f32_e32 v135, v135
	v_add_f32_e32 v134, 1.0, v134
	v_rcp_f32_e32 v134, v134
	v_pk_mul_f32 v[116:117], v[116:117], v[124:125]
	v_add_f32_e32 v135, 1.0, v135
	v_rcp_f32_e32 v135, v135
	v_mul_f32_e32 v118, v133, v118
	v_mul_f32_e32 v119, v133, v119
	v_exp_f32_e32 v118, v118
	v_pk_mul_f32 v[124:125], v[132:133], v[134:135] op_sel_hi:[0,1]
	v_pk_mul_f32 v[116:117], v[124:125], v[116:117]
	v_mul_f32_e32 v124, v133, v113
	v_exp_f32_e32 v124, v124
	v_mul_f32_e32 v114, v133, v114
	v_exp_f32_e32 v119, v119
	v_mul_f32_e32 v115, v133, v115
	v_exp_f32_e32 v114, v114
	v_exp_f32_e32 v115, v115
	v_add_f32_e32 v124, 1.0, v124
	v_add_f32_e32 v118, 1.0, v118
	v_add_f32_e32 v119, 1.0, v119
	v_rcp_f32_e32 v137, v124
	v_rcp_f32_e32 v118, v118
	v_add_f32_e32 v114, 1.0, v114
	v_rcp_f32_e32 v119, v119
	v_add_f32_e32 v115, 1.0, v115
	v_rcp_f32_e32 v114, v114
	v_rcp_f32_e32 v115, v115
	v_pk_mul_f32 v[112:113], v[112:113], v[120:121]
	v_pk_mul_f32 v[120:121], v[132:133], v[136:137] op_sel_hi:[0,1]
	v_pk_mul_f32 v[118:119], v[132:133], v[118:119] op_sel_hi:[0,1]
	v_pk_mul_f32 v[112:113], v[120:121], v[112:113]
	v_pk_mul_f32 v[118:119], v[118:119], v[126:127]
	v_pk_mul_f32 v[114:115], v[132:133], v[114:115] op_sel_hi:[0,1]
	v_pk_mul_f32 v[114:115], v[114:115], v[122:123]
	v_cvt_pk_bf16_f32 v116, v116, v117
	v_cvt_pk_bf16_f32 v117, v118, v119
	v_cvt_pk_bf16_f32 v118, v112, v113
	v_mov_b64_e32 v[112:113], s[94:95]
	s_movk_i32 s9, 0x1600
	v_cvt_pk_bf16_f32 v119, v114, v115
	v_mad_i64_i32 v[120:121], s[0:1], v154, s9, v[112:113]
	v_lshlrev_b64 v[114:115], 1, v[130:131]
	v_lshl_add_u64 v[120:121], v[120:121], 0, v[114:115]
	global_store_dwordx4 v[120:121], v[116:119], off nt
	v_pk_mul_f32 v[106:107], v[98:99], v[106:107]
	v_pk_mul_f32 v[110:111], v[102:103], v[110:111]
	v_fmamk_f32 v116, v164, 0x3a800000, v235
	v_cmp_gt_f32_e32 vcc, s86, v116
	v_mul_f32_e32 v117, 0x4b800000, v116
	v_pk_mul_f32 v[90:91], v[82:83], v[90:91]
	v_cndmask_b32_e32 v116, v116, v117, vcc
	v_rsq_f32_e32 v116, v116
	v_pk_mul_f32 v[94:95], v[86:87], v[94:95]
	v_pk_mul_f32 v[74:75], v[66:67], v[74:75]
	v_pk_mul_f32 v[78:79], v[70:71], v[78:79]
	v_mul_f32_e32 v117, 0x45800000, v116
	v_cndmask_b32_e32 v116, v116, v117, vcc
	v_mul_f32_e32 v117, 0xbfb8aa3b, v116
	v_mul_f32_e32 v119, v117, v96
	v_exp_f32_e32 v119, v119
	v_mul_f32_e32 v118, v117, v100
	v_exp_f32_e32 v118, v118
	v_mul_f32_e32 v116, v116, v116
	v_add_f32_e32 v119, 1.0, v119
	v_rcp_f32_e32 v120, v119
	v_mul_f32_e32 v119, v117, v101
	v_exp_f32_e32 v119, v119
	v_add_f32_e32 v118, 1.0, v118
	v_rcp_f32_e32 v118, v118
	v_pk_mul_f32 v[100:101], v[100:101], v[108:109]
	v_add_f32_e32 v119, 1.0, v119
	v_rcp_f32_e32 v119, v119
	v_pk_mul_f32 v[58:59], v[50:51], v[58:59]
	v_pk_mul_f32 v[62:63], v[54:55], v[62:63]
	v_pk_mul_f32 v[42:43], v[34:35], v[42:43]
	v_pk_mul_f32 v[108:109], v[116:117], v[118:119] op_sel_hi:[0,1]
	v_pk_mul_f32 v[100:101], v[108:109], v[100:101]
	v_mul_f32_e32 v108, v117, v97
	v_exp_f32_e32 v108, v108
	v_pk_mul_f32 v[96:97], v[96:97], v[104:105]
	v_pk_mul_f32 v[46:47], v[38:39], v[46:47]
	v_pk_mul_f32 v[26:27], v[18:19], v[26:27]
	v_add_f32_e32 v108, 1.0, v108
	v_rcp_f32_e32 v121, v108
	v_or_b32_e32 v108, 16, v154
	v_pk_mul_f32 v[30:31], v[22:23], v[30:31]
	v_pk_mul_f32 v[10:11], v[2:3], v[10:11]
	v_pk_mul_f32 v[104:105], v[116:117], v[120:121] op_sel_hi:[0,1]
	v_pk_mul_f32 v[104:105], v[104:105], v[96:97]
	v_mul_f32_e32 v97, v117, v98
	v_exp_f32_e32 v97, v97
	v_mul_f32_e32 v96, v117, v102
	v_exp_f32_e32 v96, v96
	v_pk_mul_f32 v[14:15], v[6:7], v[14:15]
	v_add_f32_e32 v97, 1.0, v97
	v_rcp_f32_e32 v98, v97
	v_mul_f32_e32 v97, v117, v103
	v_exp_f32_e32 v97, v97
	v_add_f32_e32 v96, 1.0, v96
	v_rcp_f32_e32 v96, v96
	s_mov_b32 s20, s12
	v_add_f32_e32 v97, 1.0, v97
	v_rcp_f32_e32 v97, v97
	s_mov_b64 s[14:15], s[42:43]
	s_mov_b64 s[18:19], s[40:41]
	v_pk_mul_f32 v[96:97], v[116:117], v[96:97] op_sel_hi:[0,1]
	v_pk_mul_f32 v[102:103], v[96:97], v[110:111]
	v_mul_f32_e32 v96, v117, v99
	v_exp_f32_e32 v96, v96
	s_nop 0
	v_add_f32_e32 v96, 1.0, v96
	v_rcp_f32_e32 v99, v96
	s_nop 0
	v_pk_mul_f32 v[96:97], v[116:117], v[98:99] op_sel_hi:[0,1]
	v_pk_mul_f32 v[106:107], v[96:97], v[106:107]
	v_cvt_pk_bf16_f32 v96, v100, v101
	v_mad_i64_i32 v[100:101], s[0:1], v108, s9, v[112:113]
	v_cvt_pk_bf16_f32 v97, v102, v103
	v_cvt_pk_bf16_f32 v98, v104, v105
	v_cvt_pk_bf16_f32 v99, v106, v107
	v_lshl_add_u64 v[100:101], v[100:101], 0, v[114:115]
	global_store_dwordx4 v[100:101], v[96:99], off nt
	s_nop 1
	v_fmamk_f32 v96, v163, 0x3a800000, v235
	v_cmp_gt_f32_e32 vcc, s86, v96
	v_mul_f32_e32 v97, 0x4b800000, v96
	s_nop 0
	v_cndmask_b32_e32 v96, v96, v97, vcc
	v_rsq_f32_e32 v96, v96
	s_nop 0
	v_mul_f32_e32 v97, 0x45800000, v96
	v_cndmask_b32_e32 v96, v96, v97, vcc
	v_mul_f32_e32 v97, 0xbfb8aa3b, v96
	v_mul_f32_e32 v99, v97, v80
	v_exp_f32_e32 v99, v99
	v_mul_f32_e32 v98, v97, v84
	v_exp_f32_e32 v98, v98
	v_mul_f32_e32 v96, v96, v96
	v_add_f32_e32 v99, 1.0, v99
	v_rcp_f32_e32 v100, v99
	v_mul_f32_e32 v99, v97, v85
	v_exp_f32_e32 v99, v99
	v_add_f32_e32 v98, 1.0, v98
	v_rcp_f32_e32 v98, v98
	v_pk_mul_f32 v[84:85], v[84:85], v[92:93]
	v_add_f32_e32 v99, 1.0, v99
	v_rcp_f32_e32 v99, v99
	s_nop 0
	v_pk_mul_f32 v[92:93], v[96:97], v[98:99] op_sel_hi:[0,1]
	v_pk_mul_f32 v[84:85], v[92:93], v[84:85]
	v_mul_f32_e32 v92, v97, v81
	v_exp_f32_e32 v92, v92
	v_pk_mul_f32 v[80:81], v[80:81], v[88:89]
	v_add_f32_e32 v92, 1.0, v92
	v_rcp_f32_e32 v101, v92
	v_or_b32_e32 v92, 32, v154
	v_pk_mul_f32 v[88:89], v[96:97], v[100:101] op_sel_hi:[0,1]
	v_pk_mul_f32 v[88:89], v[88:89], v[80:81]
	v_mul_f32_e32 v81, v97, v82
	v_exp_f32_e32 v81, v81
	v_mul_f32_e32 v80, v97, v86
	v_exp_f32_e32 v80, v80
	v_add_f32_e32 v81, 1.0, v81
	v_rcp_f32_e32 v82, v81
	v_mul_f32_e32 v81, v97, v87
	v_exp_f32_e32 v81, v81
	v_add_f32_e32 v80, 1.0, v80
	v_rcp_f32_e32 v80, v80
	v_add_f32_e32 v81, 1.0, v81
	v_rcp_f32_e32 v81, v81
	s_nop 0
	v_pk_mul_f32 v[80:81], v[96:97], v[80:81] op_sel_hi:[0,1]
	v_pk_mul_f32 v[86:87], v[80:81], v[94:95]
	v_mul_f32_e32 v80, v97, v83
	v_exp_f32_e32 v80, v80
	s_nop 0
	v_add_f32_e32 v80, 1.0, v80
	v_rcp_f32_e32 v83, v80
	s_nop 0
	v_pk_mul_f32 v[80:81], v[96:97], v[82:83] op_sel_hi:[0,1]
	v_pk_mul_f32 v[90:91], v[80:81], v[90:91]
	v_cvt_pk_bf16_f32 v80, v84, v85
	v_mad_i64_i32 v[84:85], s[0:1], v92, s9, v[112:113]
	v_cvt_pk_bf16_f32 v81, v86, v87
	v_cvt_pk_bf16_f32 v82, v88, v89
	v_cvt_pk_bf16_f32 v83, v90, v91
	v_lshl_add_u64 v[84:85], v[84:85], 0, v[114:115]
	global_store_dwordx4 v[84:85], v[80:83], off nt
	s_nop 1
	v_fmamk_f32 v80, v162, 0x3a800000, v235
	v_cmp_gt_f32_e32 vcc, s86, v80
	v_mul_f32_e32 v81, 0x4b800000, v80
	s_nop 0
	v_cndmask_b32_e32 v80, v80, v81, vcc
	v_rsq_f32_e32 v80, v80
	s_nop 0
	v_mul_f32_e32 v81, 0x45800000, v80
	v_cndmask_b32_e32 v80, v80, v81, vcc
	v_mul_f32_e32 v81, 0xbfb8aa3b, v80
	v_mul_f32_e32 v83, v81, v64
	v_exp_f32_e32 v83, v83
	v_mul_f32_e32 v82, v81, v68
	v_exp_f32_e32 v82, v82
	v_mul_f32_e32 v80, v80, v80
	v_add_f32_e32 v83, 1.0, v83
	v_rcp_f32_e32 v84, v83
	v_mul_f32_e32 v83, v81, v69
	v_exp_f32_e32 v83, v83
	v_add_f32_e32 v82, 1.0, v82
	v_rcp_f32_e32 v82, v82
	v_pk_mul_f32 v[68:69], v[68:69], v[76:77]
	v_add_f32_e32 v83, 1.0, v83
	v_rcp_f32_e32 v83, v83
	s_nop 0
	v_pk_mul_f32 v[76:77], v[80:81], v[82:83] op_sel_hi:[0,1]
	v_pk_mul_f32 v[68:69], v[76:77], v[68:69]
	v_mul_f32_e32 v76, v81, v65
	v_exp_f32_e32 v76, v76
	v_pk_mul_f32 v[64:65], v[64:65], v[72:73]
	v_add_f32_e32 v76, 1.0, v76
	v_rcp_f32_e32 v85, v76
	v_or_b32_e32 v76, 48, v154
	v_pk_mul_f32 v[72:73], v[80:81], v[84:85] op_sel_hi:[0,1]
	v_pk_mul_f32 v[72:73], v[72:73], v[64:65]
	v_mul_f32_e32 v65, v81, v66
	v_exp_f32_e32 v65, v65
	v_mul_f32_e32 v64, v81, v70
	v_exp_f32_e32 v64, v64
	v_add_f32_e32 v65, 1.0, v65
	v_rcp_f32_e32 v66, v65
	v_mul_f32_e32 v65, v81, v71
	v_exp_f32_e32 v65, v65
	v_add_f32_e32 v64, 1.0, v64
	v_rcp_f32_e32 v64, v64
	v_add_f32_e32 v65, 1.0, v65
	v_rcp_f32_e32 v65, v65
	s_nop 0
	v_pk_mul_f32 v[64:65], v[80:81], v[64:65] op_sel_hi:[0,1]
	v_pk_mul_f32 v[70:71], v[64:65], v[78:79]
	v_mul_f32_e32 v64, v81, v67
	v_exp_f32_e32 v64, v64
	s_nop 0
	v_add_f32_e32 v64, 1.0, v64
	v_rcp_f32_e32 v67, v64
	s_nop 0
	v_pk_mul_f32 v[64:65], v[80:81], v[66:67] op_sel_hi:[0,1]
	v_pk_mul_f32 v[74:75], v[64:65], v[74:75]
	v_cvt_pk_bf16_f32 v64, v68, v69
	v_mad_i64_i32 v[68:69], s[0:1], v76, s9, v[112:113]
	v_cvt_pk_bf16_f32 v65, v70, v71
	v_cvt_pk_bf16_f32 v66, v72, v73
	v_cvt_pk_bf16_f32 v67, v74, v75
	v_lshl_add_u64 v[68:69], v[68:69], 0, v[114:115]
	global_store_dwordx4 v[68:69], v[64:67], off nt
	s_nop 1
	v_fmamk_f32 v64, v161, 0x3a800000, v235
	v_cmp_gt_f32_e32 vcc, s86, v64
	v_mul_f32_e32 v66, 0x4b800000, v64
	v_add_u32_e32 v65, 0x80, v154
	v_cndmask_b32_e32 v64, v64, v66, vcc
	v_rsq_f32_e32 v64, v64
	s_nop 0
	v_mul_f32_e32 v66, 0x45800000, v64
	v_cndmask_b32_e32 v64, v64, v66, vcc
	v_mul_f32_e32 v70, 0xbfb8aa3b, v64
	v_mul_f32_e32 v67, v70, v48
	v_exp_f32_e32 v67, v67
	v_mul_f32_e32 v66, v70, v52
	v_exp_f32_e32 v66, v66
	v_mul_f32_e32 v64, v64, v64
	v_add_f32_e32 v67, 1.0, v67
	v_rcp_f32_e32 v68, v67
	v_mul_f32_e32 v67, v70, v53
	v_exp_f32_e32 v67, v67
	v_add_f32_e32 v66, 1.0, v66
	v_rcp_f32_e32 v66, v66
	v_pk_mul_f32 v[52:53], v[52:53], v[60:61]
	v_add_f32_e32 v67, 1.0, v67
	v_rcp_f32_e32 v67, v67
	s_nop 0
	v_pk_mul_f32 v[60:61], v[64:65], v[66:67] op_sel_hi:[0,1]
	v_pk_mul_f32 v[52:53], v[60:61], v[52:53]
	v_mul_f32_e32 v60, v70, v49
	v_exp_f32_e32 v60, v60
	v_pk_mul_f32 v[48:49], v[48:49], v[56:57]
	v_add_f32_e32 v60, 1.0, v60
	v_rcp_f32_e32 v69, v60
	s_nop 0
	v_pk_mul_f32 v[56:57], v[64:65], v[68:69] op_sel_hi:[0,1]
	v_pk_mul_f32 v[56:57], v[56:57], v[48:49]
	v_mul_f32_e32 v49, v70, v50
	v_exp_f32_e32 v49, v49
	v_mul_f32_e32 v48, v70, v54
	v_exp_f32_e32 v48, v48
	v_add_f32_e32 v49, 1.0, v49
	v_rcp_f32_e32 v50, v49
	v_mul_f32_e32 v49, v70, v55
	v_exp_f32_e32 v49, v49
	v_add_f32_e32 v48, 1.0, v48
	v_rcp_f32_e32 v48, v48
	v_add_f32_e32 v49, 1.0, v49
	v_rcp_f32_e32 v49, v49
	s_nop 0
	v_pk_mul_f32 v[48:49], v[64:65], v[48:49] op_sel_hi:[0,1]
	v_pk_mul_f32 v[54:55], v[48:49], v[62:63]
	v_mul_f32_e32 v48, v70, v51
	v_exp_f32_e32 v48, v48
	s_nop 0
	v_add_f32_e32 v48, 1.0, v48
	v_rcp_f32_e32 v51, v48
	s_nop 0
	v_pk_mul_f32 v[48:49], v[64:65], v[50:51] op_sel_hi:[0,1]
	v_pk_mul_f32 v[58:59], v[48:49], v[58:59]
	v_cvt_pk_bf16_f32 v48, v52, v53
	v_mad_i64_i32 v[52:53], s[0:1], v65, s9, v[112:113]
	v_cvt_pk_bf16_f32 v49, v54, v55
	v_cvt_pk_bf16_f32 v50, v56, v57
	v_cvt_pk_bf16_f32 v51, v58, v59
	v_lshl_add_u64 v[52:53], v[52:53], 0, v[114:115]
	global_store_dwordx4 v[52:53], v[48:51], off nt
	s_nop 1
	v_fmamk_f32 v48, v160, 0x3a800000, v235
	v_cmp_gt_f32_e32 vcc, s86, v48
	v_mul_f32_e32 v49, 0x4b800000, v48
	s_nop 0
	v_cndmask_b32_e32 v48, v48, v49, vcc
	v_rsq_f32_e32 v48, v48
	s_nop 0
	v_mul_f32_e32 v49, 0x45800000, v48
	v_cndmask_b32_e32 v48, v48, v49, vcc
	v_mul_f32_e32 v49, 0xbfb8aa3b, v48
	v_mul_f32_e32 v51, v49, v32
	v_exp_f32_e32 v51, v51
	v_mul_f32_e32 v50, v49, v36
	v_exp_f32_e32 v50, v50
	v_mul_f32_e32 v48, v48, v48
	v_add_f32_e32 v51, 1.0, v51
	v_rcp_f32_e32 v52, v51
	v_mul_f32_e32 v51, v49, v37
	v_exp_f32_e32 v51, v51
	v_add_f32_e32 v50, 1.0, v50
	v_rcp_f32_e32 v50, v50
	v_pk_mul_f32 v[36:37], v[36:37], v[44:45]
	v_add_f32_e32 v51, 1.0, v51
	v_rcp_f32_e32 v51, v51
	s_nop 0
	v_pk_mul_f32 v[44:45], v[48:49], v[50:51] op_sel_hi:[0,1]
	v_pk_mul_f32 v[36:37], v[44:45], v[36:37]
	v_mul_f32_e32 v44, v49, v33
	v_exp_f32_e32 v44, v44
	v_pk_mul_f32 v[32:33], v[32:33], v[40:41]
	v_add_f32_e32 v44, 1.0, v44
	v_rcp_f32_e32 v53, v44
	v_add_u32_e32 v44, 0x90, v154
	v_pk_mul_f32 v[40:41], v[48:49], v[52:53] op_sel_hi:[0,1]
	v_pk_mul_f32 v[40:41], v[40:41], v[32:33]
	v_mul_f32_e32 v33, v49, v34
	v_exp_f32_e32 v33, v33
	v_mul_f32_e32 v32, v49, v38
	v_exp_f32_e32 v32, v32
	v_add_f32_e32 v33, 1.0, v33
	v_rcp_f32_e32 v34, v33
	v_mul_f32_e32 v33, v49, v39
	v_exp_f32_e32 v33, v33
	v_add_f32_e32 v32, 1.0, v32
	v_rcp_f32_e32 v32, v32
	v_add_f32_e32 v33, 1.0, v33
	v_rcp_f32_e32 v33, v33
	s_nop 0
	v_pk_mul_f32 v[32:33], v[48:49], v[32:33] op_sel_hi:[0,1]
	v_pk_mul_f32 v[38:39], v[32:33], v[46:47]
	v_mul_f32_e32 v32, v49, v35
	v_exp_f32_e32 v32, v32
	s_nop 0
	v_add_f32_e32 v32, 1.0, v32
	v_rcp_f32_e32 v35, v32
	s_nop 0
	v_pk_mul_f32 v[32:33], v[48:49], v[34:35] op_sel_hi:[0,1]
	v_pk_mul_f32 v[42:43], v[32:33], v[42:43]
	v_cvt_pk_bf16_f32 v32, v36, v37
	v_mad_i64_i32 v[36:37], s[0:1], v44, s9, v[112:113]
	v_cvt_pk_bf16_f32 v33, v38, v39
	v_cvt_pk_bf16_f32 v34, v40, v41
	v_cvt_pk_bf16_f32 v35, v42, v43
	v_lshl_add_u64 v[36:37], v[36:37], 0, v[114:115]
	global_store_dwordx4 v[36:37], v[32:35], off nt
	s_nop 1
	v_fmamk_f32 v32, v159, 0x3a800000, v235
	v_cmp_gt_f32_e32 vcc, s86, v32
	v_mul_f32_e32 v33, 0x4b800000, v32
	s_nop 0
	v_cndmask_b32_e32 v32, v32, v33, vcc
	v_rsq_f32_e32 v32, v32
	s_nop 0
	v_mul_f32_e32 v33, 0x45800000, v32
	v_cndmask_b32_e32 v32, v32, v33, vcc
	v_mul_f32_e32 v33, 0xbfb8aa3b, v32
	v_mul_f32_e32 v35, v33, v16
	v_exp_f32_e32 v35, v35
	v_mul_f32_e32 v34, v33, v20
	v_exp_f32_e32 v34, v34
	v_mul_f32_e32 v32, v32, v32
	v_add_f32_e32 v35, 1.0, v35
	v_rcp_f32_e32 v36, v35
	v_mul_f32_e32 v35, v33, v21
	v_exp_f32_e32 v35, v35
	v_add_f32_e32 v34, 1.0, v34
	v_rcp_f32_e32 v34, v34
	v_pk_mul_f32 v[20:21], v[20:21], v[28:29]
	v_add_f32_e32 v35, 1.0, v35
	v_rcp_f32_e32 v35, v35
	s_nop 0
	v_pk_mul_f32 v[28:29], v[32:33], v[34:35] op_sel_hi:[0,1]
	v_pk_mul_f32 v[20:21], v[28:29], v[20:21]
	v_mul_f32_e32 v28, v33, v17
	v_exp_f32_e32 v28, v28
	v_pk_mul_f32 v[16:17], v[16:17], v[24:25]
	v_add_f32_e32 v28, 1.0, v28
	v_rcp_f32_e32 v37, v28
	v_add_u32_e32 v28, 0xa0, v154
	v_pk_mul_f32 v[24:25], v[32:33], v[36:37] op_sel_hi:[0,1]
	v_pk_mul_f32 v[24:25], v[24:25], v[16:17]
	v_mul_f32_e32 v17, v33, v18
	v_exp_f32_e32 v17, v17
	v_mul_f32_e32 v16, v33, v22
	v_exp_f32_e32 v16, v16
	v_add_f32_e32 v17, 1.0, v17
	v_rcp_f32_e32 v18, v17
	v_mul_f32_e32 v17, v33, v23
	v_exp_f32_e32 v17, v17
	v_add_f32_e32 v16, 1.0, v16
	v_rcp_f32_e32 v16, v16
	v_add_f32_e32 v17, 1.0, v17
	v_rcp_f32_e32 v17, v17
	s_nop 0
	v_pk_mul_f32 v[16:17], v[32:33], v[16:17] op_sel_hi:[0,1]
	v_pk_mul_f32 v[22:23], v[16:17], v[30:31]
	v_mul_f32_e32 v16, v33, v19
	v_exp_f32_e32 v16, v16
	s_nop 0
	v_add_f32_e32 v16, 1.0, v16
	v_rcp_f32_e32 v19, v16
	s_nop 0
	v_pk_mul_f32 v[16:17], v[32:33], v[18:19] op_sel_hi:[0,1]
	v_pk_mul_f32 v[26:27], v[16:17], v[26:27]
	v_cvt_pk_bf16_f32 v16, v20, v21
	v_mad_i64_i32 v[20:21], s[0:1], v28, s9, v[112:113]
	v_cvt_pk_bf16_f32 v17, v22, v23
	v_cvt_pk_bf16_f32 v18, v24, v25
	v_cvt_pk_bf16_f32 v19, v26, v27
	v_lshl_add_u64 v[20:21], v[20:21], 0, v[114:115]
	global_store_dwordx4 v[20:21], v[16:19], off nt
	s_nop 1
	v_fmamk_f32 v16, v155, 0x3a800000, v235
	v_cmp_gt_f32_e32 vcc, s86, v16
	v_mul_f32_e32 v17, 0x4b800000, v16
	s_nop 0
	v_cndmask_b32_e32 v16, v16, v17, vcc
	v_rsq_f32_e32 v16, v16
	s_nop 0
	v_mul_f32_e32 v17, 0x45800000, v16
	v_cndmask_b32_e32 v16, v16, v17, vcc
	v_mul_f32_e32 v17, 0xbfb8aa3b, v16
	v_mul_f32_e32 v19, v17, v0
	v_exp_f32_e32 v19, v19
	v_mul_f32_e32 v18, v17, v4
	v_exp_f32_e32 v18, v18
	v_mul_f32_e32 v16, v16, v16
	v_add_f32_e32 v19, 1.0, v19
	v_rcp_f32_e32 v20, v19
	v_mul_f32_e32 v19, v17, v5
	v_exp_f32_e32 v19, v19
	v_add_f32_e32 v18, 1.0, v18
	v_rcp_f32_e32 v18, v18
	v_pk_mul_f32 v[4:5], v[4:5], v[12:13]
	v_add_f32_e32 v19, 1.0, v19
	v_rcp_f32_e32 v19, v19
	s_and_b64 vcc, exec, s[38:39]
	v_pk_mul_f32 v[12:13], v[16:17], v[18:19] op_sel_hi:[0,1]
	v_pk_mul_f32 v[4:5], v[12:13], v[4:5]
	v_mul_f32_e32 v12, v17, v1
	v_exp_f32_e32 v12, v12
	v_pk_mul_f32 v[0:1], v[0:1], v[8:9]
	v_add_f32_e32 v12, 1.0, v12
	v_rcp_f32_e32 v21, v12
	v_add_u32_e32 v12, 0xb0, v154
	v_pk_mul_f32 v[8:9], v[16:17], v[20:21] op_sel_hi:[0,1]
	v_pk_mul_f32 v[8:9], v[8:9], v[0:1]
	v_mul_f32_e32 v1, v17, v2
	v_exp_f32_e32 v1, v1
	v_mul_f32_e32 v0, v17, v6
	v_exp_f32_e32 v0, v0
	v_add_f32_e32 v1, 1.0, v1
	v_rcp_f32_e32 v2, v1
	v_mul_f32_e32 v1, v17, v7
	v_exp_f32_e32 v1, v1
	v_add_f32_e32 v0, 1.0, v0
	v_rcp_f32_e32 v0, v0
	v_add_f32_e32 v1, 1.0, v1
	v_rcp_f32_e32 v1, v1
	s_nop 0
	v_pk_mul_f32 v[0:1], v[16:17], v[0:1] op_sel_hi:[0,1]
	v_pk_mul_f32 v[6:7], v[0:1], v[14:15]
	v_mul_f32_e32 v0, v17, v3
	v_exp_f32_e32 v0, v0
	s_nop 0
	v_add_f32_e32 v0, 1.0, v0
	v_rcp_f32_e32 v3, v0
	s_nop 0
	v_pk_mul_f32 v[0:1], v[16:17], v[2:3] op_sel_hi:[0,1]
	v_pk_mul_f32 v[10:11], v[0:1], v[10:11]
	v_cvt_pk_bf16_f32 v0, v4, v5
	v_mad_i64_i32 v[4:5], s[0:1], v12, s9, v[112:113]
	v_cvt_pk_bf16_f32 v1, v6, v7
	v_cvt_pk_bf16_f32 v2, v8, v9
	v_cvt_pk_bf16_f32 v3, v10, v11
	v_lshl_add_u64 v[4:5], v[4:5], 0, v[114:115]
	s_mov_b32 s0, s8
	global_store_dwordx4 v[4:5], v[0:3], off nt
	s_cbranch_vccz .LBB0_388
	s_waitcnt vmcnt(0)
	v_readlane_b32 s20, v255, 27
